# every 32-MFMA block of the six GEMM K-loops aligned to 8 bytes (.p2align 3 before the setprio/barrier pair, pad on the load-segment side)
# speedup vs baseline: 1.0016x; 1.0016x over previous
; #define PG8_STAGE(bufoff, gbase, voff) do { _Pragma("unroll") for (int _i = 0; _i < 2; ++_i) \
;         __builtin_amdgcn_global_load_lds((const unsigned*)((const char*)(gbase) + (voff)[_i]), (PG8_LAS unsigned*)(lds + (bufoff) + ldsw + _i * 8192), 16, 0, 0); } while (0)
; #define PG8_LDA(dst, b, h) do { _Pragma("unroll") for (int m = 0; m < 4; ++m) _Pragma("unroll") for (int k = 0; k < 2; ++k) dst[m][k] = *(const PG8_LAS bf16x8*)(lds + PG8_SA(b, h) + aoff + m * 2048 + k * 1024); } while (0)
; #define PG8_LDB(dst, b, h) do { _Pragma("unroll") for (int n = 0; n < 2; ++n) _Pragma("unroll") for (int k = 0; k < 2; ++k) dst[n][k] = *(const PG8_LAS bf16x8*)(lds + PG8_SB(b, h) + boff + n * 2048 + k * 1024); } while (0)
; #define PG8_WAIT_L(n) asm volatile("s_waitcnt lgkmcnt(" #n ")" ::: "memory")
; #define PG8_WAIT_V_SEL(sel) asm volatile("s_cmp_eq_u32 %0, 0\n\ts_cbranch_scc1 .Lw8_%=\n\ts_waitcnt vmcnt(22)\n\ts_branch .Lwd_%=\n.Lw8_%=:\n\ts_waitcnt vmcnt(8)\n.Lwd_%=:" :: "s"(sel) : "memory", "scc")
; #define PG8_BAR __builtin_amdgcn_s_barrier()
; #define PG8_SCHED __builtin_amdgcn_sched_barrier(0)
;     ...
;             const bool last = (t == nt * KREP - 2);
;             const int t1w = KREP > 1 ? ((t + 1) & (nt - 1)) : t + 1, t2w = KREP > 1 ? ((t + 2) & (nt - 1)) : t + 2;
;             const char* a1 = cA + (size_t)t1w * kstep;
;             const char* a2 = last ? nA : cA + (size_t)t2w * kstep; const char* b2 = last ? nB : cB + (size_t)t2w * kstep;
;             const char* a3 = a2 + kstep; const char* b3 = b2 + kstep;
;             if (last && has_next) S.a_ready(nxt);
;             const int relax = __builtin_amdgcn_readfirstlane((MK_RELAXW && t == 0 && ui > 0) ? 1 : 0);
;             if constexpr (SP2) {
;             PG8_LDB(B0, 0, 0); PG8_LDB(B1, 0, 1); PG8_SCHED; PG8_LDA(At, 0, 0); PG8_STAGE(PG8_SA(1, 1), a1 + hstep, voffA);
;             PG8_WAIT_V_SEL(relax);
;             PG8_WAIT_L(0); PG8_BAR; PG8_MMA(0, 0, At, B0); PG8_MMA(0, 1, At, B1); PG8_BAR; PG8_SCHED;
;             PG8_LDA(At, 0, 1); PG8_STAGE(PG8_SB(0, 0), b2, voffB); PG8_STAGE(PG8_SB(0, 1), b2 + hstep, voffB); PG8_STAGE(PG8_SA(0, 0), a2, voffA);
;             PG8_WAIT_V_SEL(relax);
;             PG8_WAIT_L(0); PG8_BAR; PG8_MMA(1, 0, At, B0); PG8_MMA(1, 1, At, B1); PG8_BAR; PG8_SCHED;
.LBB0_234:
	s_add_u32 s0, s78, 0xfff80080
	s_addc_u32 s1, s79, -1
	s_add_i32 s40, 0, 0x10000
	s_cmp_eq_u32 s37, 28
	s_cselect_b32 s83, s19, s1
	s_cselect_b32 s82, s20, s0
	s_cselect_b32 s81, s24, s35
	s_cselect_b32 s80, s31, s33
	s_add_i32 s41, 0, 0x14000
	ds_read_b128 v[142:145], v168
	ds_read_b128 v[146:149], v168 offset:1024
	ds_read_b128 v[150:153], v168 offset:2048
	ds_read_b128 v[154:157], v168 offset:3072
	ds_read_b128 v[158:161], v168 offset:16384
	ds_read_b128 v[162:165], v168 offset:17408
	ds_read_b128 v[174:177], v168 offset:18432
	ds_read_b128 v[188:191], v168 offset:19456
	s_add_i32 m0, s75, 0xc000
	ds_read_b128 v[198:201], v196
	ds_read_b128 v[202:205], v196 offset:1024
	ds_read_b128 v[206:209], v196 offset:2048
	ds_read_b128 v[210:213], v196 offset:3072
	ds_read_b128 v[214:217], v196 offset:4096
	ds_read_b128 v[218:221], v196 offset:5120
	ds_read_b128 v[222:225], v196 offset:6144
	ds_read_b128 v[226:229], v196 offset:7168
	global_load_lds_dwordx4 v138, s[78:79]
	s_add_i32 m0, s75, 0xe000
	s_nop 0
	global_load_lds_dwordx4 v140, s[78:79]
	s_waitcnt vmcnt(8)
	s_waitcnt lgkmcnt(0)
	.p2align 3
	s_setprio 1
	s_barrier
	v_mfma_f32_16x16x32_bf16 v[126:129], v[142:145], v[198:201], v[126:129]
	v_mfma_f32_16x16x32_bf16 v[126:129], v[146:149], v[202:205], v[126:129]
	v_mfma_f32_16x16x32_bf16 v[122:125], v[142:145], v[206:209], v[122:125]
	v_mfma_f32_16x16x32_bf16 v[122:125], v[146:149], v[210:213], v[122:125]
	v_mfma_f32_16x16x32_bf16 v[118:121], v[142:145], v[214:217], v[118:121]
	v_mfma_f32_16x16x32_bf16 v[118:121], v[146:149], v[218:221], v[118:121]
	v_mfma_f32_16x16x32_bf16 v[114:117], v[142:145], v[222:225], v[114:117]
	v_mfma_f32_16x16x32_bf16 v[114:117], v[146:149], v[226:229], v[114:117]
	v_mfma_f32_16x16x32_bf16 v[98:101], v[150:153], v[222:225], v[98:101]
	v_mfma_f32_16x16x32_bf16 v[98:101], v[154:157], v[226:229], v[98:101]
	v_mfma_f32_16x16x32_bf16 v[102:105], v[150:153], v[214:217], v[102:105]
	v_mfma_f32_16x16x32_bf16 v[102:105], v[154:157], v[218:221], v[102:105]
	v_mfma_f32_16x16x32_bf16 v[106:109], v[150:153], v[206:209], v[106:109]
	v_mfma_f32_16x16x32_bf16 v[106:109], v[154:157], v[210:213], v[106:109]
	v_mfma_f32_16x16x32_bf16 v[110:113], v[150:153], v[198:201], v[110:113]
	v_mfma_f32_16x16x32_bf16 v[110:113], v[154:157], v[202:205], v[110:113]
	v_mfma_f32_16x16x32_bf16 v[82:85], v[158:161], v[198:201], v[82:85]
	v_mfma_f32_16x16x32_bf16 v[82:85], v[162:165], v[202:205], v[82:85]
	v_mfma_f32_16x16x32_bf16 v[70:73], v[158:161], v[206:209], v[70:73]
	v_mfma_f32_16x16x32_bf16 v[70:73], v[162:165], v[210:213], v[70:73]
	v_mfma_f32_16x16x32_bf16 v[66:69], v[158:161], v[214:217], v[66:69]
	v_mfma_f32_16x16x32_bf16 v[66:69], v[162:165], v[218:221], v[66:69]
	v_mfma_f32_16x16x32_bf16 v[58:61], v[158:161], v[222:225], v[58:61]
	v_mfma_f32_16x16x32_bf16 v[58:61], v[162:165], v[226:229], v[58:61]
	v_mfma_f32_16x16x32_bf16 v[18:21], v[174:177], v[222:225], v[18:21]
	v_mfma_f32_16x16x32_bf16 v[18:21], v[188:191], v[226:229], v[18:21]
	v_mfma_f32_16x16x32_bf16 v[22:25], v[174:177], v[214:217], v[22:25]
	v_mfma_f32_16x16x32_bf16 v[22:25], v[188:191], v[218:221], v[22:25]
	v_mfma_f32_16x16x32_bf16 v[26:29], v[174:177], v[206:209], v[26:29]
	v_mfma_f32_16x16x32_bf16 v[26:29], v[188:191], v[210:213], v[26:29]
	v_mfma_f32_16x16x32_bf16 v[30:33], v[174:177], v[198:201], v[30:33]
	v_mfma_f32_16x16x32_bf16 v[30:33], v[188:191], v[202:205], v[30:33]
	s_barrier
	s_setprio 0
	s_add_i32 s0, s40, s87
	s_mov_b32 m0, s0
	ds_read_b128 v[198:201], v196 offset:16384
	ds_read_b128 v[202:205], v196 offset:17408
	ds_read_b128 v[206:209], v196 offset:18432
	ds_read_b128 v[210:213], v196 offset:19456
	ds_read_b128 v[214:217], v196 offset:20480
	ds_read_b128 v[218:221], v196 offset:21504
	ds_read_b128 v[222:225], v196 offset:22528
	ds_read_b128 v[226:229], v196 offset:23552
	global_load_lds_dwordx4 v182, s[80:81]
	s_add_i32 m0, s0, 0x2000
	s_add_u32 s0, s80, 0x80000
	s_addc_u32 s1, s81, 0
	s_add_i32 s40, s41, s87
	global_load_lds_dwordx4 v134, s[80:81]
	s_mov_b32 m0, s40
	s_nop 0
	global_load_lds_dwordx4 v182, s[0:1]
	s_add_i32 m0, s40, 0x2000
	s_nop 0
	global_load_lds_dwordx4 v134, s[0:1]
	s_mov_b32 m0, s75
	s_nop 0
	global_load_lds_dwordx4 v130, s[82:83]
	s_mov_b32 m0, s88
	s_nop 0
	global_load_lds_dwordx4 v132, s[82:83]
	s_waitcnt vmcnt(8)
	s_waitcnt lgkmcnt(0)
	.p2align 3
	s_setprio 1
	s_barrier
	v_mfma_f32_16x16x32_bf16 v[94:97], v[142:145], v[198:201], v[94:97]
	v_mfma_f32_16x16x32_bf16 v[94:97], v[146:149], v[202:205], v[94:97]
	v_mfma_f32_16x16x32_bf16 v[90:93], v[142:145], v[206:209], v[90:93]
	v_mfma_f32_16x16x32_bf16 v[90:93], v[146:149], v[210:213], v[90:93]
	v_mfma_f32_16x16x32_bf16 v[86:89], v[142:145], v[214:217], v[86:89]
	v_mfma_f32_16x16x32_bf16 v[86:89], v[146:149], v[218:221], v[86:89]
	v_mfma_f32_16x16x32_bf16 v[78:81], v[142:145], v[222:225], v[78:81]
	v_mfma_f32_16x16x32_bf16 v[78:81], v[146:149], v[226:229], v[78:81]
	v_mfma_f32_16x16x32_bf16 v[50:53], v[150:153], v[222:225], v[50:53]
	v_mfma_f32_16x16x32_bf16 v[50:53], v[154:157], v[226:229], v[50:53]
	v_mfma_f32_16x16x32_bf16 v[54:57], v[150:153], v[214:217], v[54:57]
	v_mfma_f32_16x16x32_bf16 v[54:57], v[154:157], v[218:221], v[54:57]
	v_mfma_f32_16x16x32_bf16 v[62:65], v[150:153], v[206:209], v[62:65]
	v_mfma_f32_16x16x32_bf16 v[62:65], v[154:157], v[210:213], v[62:65]
	v_mfma_f32_16x16x32_bf16 v[74:77], v[150:153], v[198:201], v[74:77]
	v_mfma_f32_16x16x32_bf16 v[74:77], v[154:157], v[202:205], v[74:77]
	v_mfma_f32_16x16x32_bf16 v[46:49], v[158:161], v[198:201], v[46:49]
	v_mfma_f32_16x16x32_bf16 v[46:49], v[162:165], v[202:205], v[46:49]
	v_mfma_f32_16x16x32_bf16 v[42:45], v[158:161], v[206:209], v[42:45]
	v_mfma_f32_16x16x32_bf16 v[42:45], v[162:165], v[210:213], v[42:45]
	v_mfma_f32_16x16x32_bf16 v[38:41], v[158:161], v[214:217], v[38:41]
	v_mfma_f32_16x16x32_bf16 v[38:41], v[162:165], v[218:221], v[38:41]
	v_mfma_f32_16x16x32_bf16 v[34:37], v[158:161], v[222:225], v[34:37]
	v_mfma_f32_16x16x32_bf16 v[34:37], v[162:165], v[226:229], v[34:37]
	v_mfma_f32_16x16x32_bf16 v[2:5], v[174:177], v[222:225], v[2:5]
	v_mfma_f32_16x16x32_bf16 v[2:5], v[188:191], v[226:229], v[2:5]
	v_mfma_f32_16x16x32_bf16 v[6:9], v[174:177], v[214:217], v[6:9]
	v_mfma_f32_16x16x32_bf16 v[6:9], v[188:191], v[218:221], v[6:9]
	v_mfma_f32_16x16x32_bf16 v[10:13], v[174:177], v[206:209], v[10:13]
	v_mfma_f32_16x16x32_bf16 v[10:13], v[188:191], v[210:213], v[10:13]
	v_mfma_f32_16x16x32_bf16 v[14:17], v[174:177], v[198:201], v[14:17]
	v_mfma_f32_16x16x32_bf16 v[14:17], v[188:191], v[202:205], v[14:17]
	s_barrier
; #define PG8_STAGE(bufoff, gbase, voff) do { _Pragma("unroll") for (int _i = 0; _i < 2; ++_i) \
;         __builtin_amdgcn_global_load_lds((const unsigned*)((const char*)(gbase) + (voff)[_i]), (PG8_LAS unsigned*)(lds + (bufoff) + ldsw + _i * 8192), 16, 0, 0); } while (0)
; #define PG8_LDA(dst, b, h) do { _Pragma("unroll") for (int m = 0; m < 4; ++m) _Pragma("unroll") for (int k = 0; k < 2; ++k) dst[m][k] = *(const PG8_LAS bf16x8*)(lds + PG8_SA(b, h) + aoff + m * 2048 + k * 1024); } while (0)
; #define PG8_LDB(dst, b, h) do { _Pragma("unroll") for (int n = 0; n < 2; ++n) _Pragma("unroll") for (int k = 0; k < 2; ++k) dst[n][k] = *(const PG8_LAS bf16x8*)(lds + PG8_SB(b, h) + boff + n * 2048 + k * 1024); } while (0)
; #define PG8_WAIT_V(n) asm volatile("s_waitcnt vmcnt(" #n ")" ::: "memory")
; #define PG8_WAIT_L(n) asm volatile("s_waitcnt lgkmcnt(" #n ")" ::: "memory")
; #define PG8_BAR __builtin_amdgcn_s_barrier()
; #define PG8_SCHED __builtin_amdgcn_sched_barrier(0)
;     ...
;             PG8_WAIT_L(0); PG8_BAR; PG8_MMA(1, 0, At, B0); PG8_MMA(1, 1, At, B1); PG8_BAR; PG8_SCHED;
;             PG8_LDB(B0, 1, 0); PG8_LDB(B1, 1, 1); PG8_SCHED; PG8_LDA(At, 1, 0); PG8_STAGE(PG8_SA(0, 1), a2 + hstep, voffA);
;             PG8_WAIT_V(8); PG8_WAIT_L(0); PG8_BAR; PG8_MMA(0, 0, At, B0); PG8_MMA(0, 1, At, B1); PG8_BAR; PG8_SCHED;
;             PG8_LDA(At, 1, 1); PG8_STAGE(PG8_SB(1, 0), b3, voffB); PG8_STAGE(PG8_SB(1, 1), b3 + hstep, voffB); PG8_STAGE(PG8_SA(1, 0), a3, voffA);
;             PG8_WAIT_V(8); PG8_WAIT_L(0); PG8_BAR; PG8_MMA(1, 0, At, B0); PG8_MMA(1, 1, At, B1); PG8_BAR; PG8_SCHED;
	s_setprio 0
	s_add_i32 s40, 0, 0x18000
	s_add_i32 s41, 0, 0x1c000
	ds_read_b128 v[142:145], v168 offset:32768
	ds_read_b128 v[146:149], v168 offset:33792
	ds_read_b128 v[150:153], v168 offset:34816
	ds_read_b128 v[154:157], v168 offset:35840
	ds_read_b128 v[158:161], v168 offset:49152
	ds_read_b128 v[162:165], v168 offset:50176
	ds_read_b128 v[174:177], v168 offset:51200
	ds_read_b128 v[188:191], v168 offset:52224
	s_add_u32 s0, s82, 0x80000
	s_addc_u32 s1, s83, 0
	s_mov_b32 m0, s89
	ds_read_b128 v[198:201], v196 offset:32768
	ds_read_b128 v[202:205], v196 offset:33792
	ds_read_b128 v[206:209], v196 offset:34816
	ds_read_b128 v[210:213], v196 offset:35840
	ds_read_b128 v[214:217], v196 offset:36864
	ds_read_b128 v[218:221], v196 offset:37888
	ds_read_b128 v[222:225], v196 offset:38912
	ds_read_b128 v[226:229], v196 offset:39936
	global_load_lds_dwordx4 v130, s[0:1]
	s_mov_b32 m0, s90
	s_nop 0
	global_load_lds_dwordx4 v132, s[0:1]
	s_waitcnt vmcnt(8)
	s_waitcnt lgkmcnt(0)
	.p2align 3
	s_setprio 1
	s_barrier
	v_mfma_f32_16x16x32_bf16 v[126:129], v[142:145], v[198:201], v[126:129]
	v_mfma_f32_16x16x32_bf16 v[126:129], v[146:149], v[202:205], v[126:129]
	v_mfma_f32_16x16x32_bf16 v[122:125], v[142:145], v[206:209], v[122:125]
	v_mfma_f32_16x16x32_bf16 v[122:125], v[146:149], v[210:213], v[122:125]
	v_mfma_f32_16x16x32_bf16 v[118:121], v[142:145], v[214:217], v[118:121]
	v_mfma_f32_16x16x32_bf16 v[118:121], v[146:149], v[218:221], v[118:121]
	v_mfma_f32_16x16x32_bf16 v[114:117], v[142:145], v[222:225], v[114:117]
	v_mfma_f32_16x16x32_bf16 v[114:117], v[146:149], v[226:229], v[114:117]
	v_mfma_f32_16x16x32_bf16 v[98:101], v[150:153], v[222:225], v[98:101]
	v_mfma_f32_16x16x32_bf16 v[98:101], v[154:157], v[226:229], v[98:101]
	v_mfma_f32_16x16x32_bf16 v[102:105], v[150:153], v[214:217], v[102:105]
	v_mfma_f32_16x16x32_bf16 v[102:105], v[154:157], v[218:221], v[102:105]
	v_mfma_f32_16x16x32_bf16 v[106:109], v[150:153], v[206:209], v[106:109]
	v_mfma_f32_16x16x32_bf16 v[106:109], v[154:157], v[210:213], v[106:109]
	v_mfma_f32_16x16x32_bf16 v[110:113], v[150:153], v[198:201], v[110:113]
	v_mfma_f32_16x16x32_bf16 v[110:113], v[154:157], v[202:205], v[110:113]
	v_mfma_f32_16x16x32_bf16 v[82:85], v[158:161], v[198:201], v[82:85]
	v_mfma_f32_16x16x32_bf16 v[82:85], v[162:165], v[202:205], v[82:85]
	v_mfma_f32_16x16x32_bf16 v[70:73], v[158:161], v[206:209], v[70:73]
	v_mfma_f32_16x16x32_bf16 v[70:73], v[162:165], v[210:213], v[70:73]
	v_mfma_f32_16x16x32_bf16 v[66:69], v[158:161], v[214:217], v[66:69]
	v_mfma_f32_16x16x32_bf16 v[66:69], v[162:165], v[218:221], v[66:69]
	v_mfma_f32_16x16x32_bf16 v[58:61], v[158:161], v[222:225], v[58:61]
	v_mfma_f32_16x16x32_bf16 v[58:61], v[162:165], v[226:229], v[58:61]
	v_mfma_f32_16x16x32_bf16 v[18:21], v[174:177], v[222:225], v[18:21]
	v_mfma_f32_16x16x32_bf16 v[18:21], v[188:191], v[226:229], v[18:21]
	v_mfma_f32_16x16x32_bf16 v[22:25], v[174:177], v[214:217], v[22:25]
	v_mfma_f32_16x16x32_bf16 v[22:25], v[188:191], v[218:221], v[22:25]
	v_mfma_f32_16x16x32_bf16 v[26:29], v[174:177], v[206:209], v[26:29]
	v_mfma_f32_16x16x32_bf16 v[26:29], v[188:191], v[210:213], v[26:29]
	v_mfma_f32_16x16x32_bf16 v[30:33], v[174:177], v[198:201], v[30:33]
	v_mfma_f32_16x16x32_bf16 v[30:33], v[188:191], v[202:205], v[30:33]
	s_barrier
	s_setprio 0
	s_add_i32 s0, s40, s87
	s_mov_b32 m0, s0
	ds_read_b128 v[198:201], v196 offset:49152
	ds_read_b128 v[202:205], v196 offset:50176
	ds_read_b128 v[206:209], v196 offset:51200
	ds_read_b128 v[210:213], v196 offset:52224
	ds_read_b128 v[214:217], v196 offset:53248
	ds_read_b128 v[218:221], v196 offset:54272
	ds_read_b128 v[222:225], v196 offset:55296
	ds_read_b128 v[226:229], v196 offset:56320
	s_add_u32 s100, s80, 0x80
	s_addc_u32 s101, s81, 0
	global_load_lds_dwordx4 v182, s[100:101]
	s_add_i32 m0, s0, 0x2000
	s_add_u32 s0, s80, 0x80080
	s_addc_u32 s1, s81, 0
	s_add_i32 s40, s41, s87
	global_load_lds_dwordx4 v134, s[100:101]
	s_mov_b32 m0, s40
	s_nop 0
	global_load_lds_dwordx4 v182, s[0:1]
	s_add_i32 m0, s40, 0x2000
	s_nop 0
	global_load_lds_dwordx4 v134, s[0:1]
	s_mov_b32 m0, s94
	s_nop 0
	s_add_u32 s100, s82, 0x80
	s_addc_u32 s101, s83, 0
	global_load_lds_dwordx4 v130, s[100:101]
	s_mov_b32 m0, s95
	s_nop 0
	global_load_lds_dwordx4 v132, s[100:101]
	s_waitcnt vmcnt(8)
	s_waitcnt lgkmcnt(0)
	.p2align 3
	s_setprio 1
	s_barrier
	v_mfma_f32_16x16x32_bf16 v[94:97], v[142:145], v[198:201], v[94:97]
	v_mfma_f32_16x16x32_bf16 v[94:97], v[146:149], v[202:205], v[94:97]
	v_mfma_f32_16x16x32_bf16 v[90:93], v[142:145], v[206:209], v[90:93]
	v_mfma_f32_16x16x32_bf16 v[90:93], v[146:149], v[210:213], v[90:93]
	v_mfma_f32_16x16x32_bf16 v[86:89], v[142:145], v[214:217], v[86:89]
	v_mfma_f32_16x16x32_bf16 v[86:89], v[146:149], v[218:221], v[86:89]
	v_mfma_f32_16x16x32_bf16 v[78:81], v[142:145], v[222:225], v[78:81]
	v_mfma_f32_16x16x32_bf16 v[78:81], v[146:149], v[226:229], v[78:81]
	v_mfma_f32_16x16x32_bf16 v[50:53], v[150:153], v[222:225], v[50:53]
	v_mfma_f32_16x16x32_bf16 v[50:53], v[154:157], v[226:229], v[50:53]
	v_mfma_f32_16x16x32_bf16 v[54:57], v[150:153], v[214:217], v[54:57]
	v_mfma_f32_16x16x32_bf16 v[54:57], v[154:157], v[218:221], v[54:57]
	v_mfma_f32_16x16x32_bf16 v[62:65], v[150:153], v[206:209], v[62:65]
	v_mfma_f32_16x16x32_bf16 v[62:65], v[154:157], v[210:213], v[62:65]
	v_mfma_f32_16x16x32_bf16 v[74:77], v[150:153], v[198:201], v[74:77]
	v_mfma_f32_16x16x32_bf16 v[74:77], v[154:157], v[202:205], v[74:77]
	v_mfma_f32_16x16x32_bf16 v[46:49], v[158:161], v[198:201], v[46:49]
	v_mfma_f32_16x16x32_bf16 v[46:49], v[162:165], v[202:205], v[46:49]
	v_mfma_f32_16x16x32_bf16 v[42:45], v[158:161], v[206:209], v[42:45]
	v_mfma_f32_16x16x32_bf16 v[42:45], v[162:165], v[210:213], v[42:45]
	v_mfma_f32_16x16x32_bf16 v[38:41], v[158:161], v[214:217], v[38:41]
	v_mfma_f32_16x16x32_bf16 v[38:41], v[162:165], v[218:221], v[38:41]
	v_mfma_f32_16x16x32_bf16 v[34:37], v[158:161], v[222:225], v[34:37]
	v_mfma_f32_16x16x32_bf16 v[34:37], v[162:165], v[226:229], v[34:37]
	v_mfma_f32_16x16x32_bf16 v[2:5], v[174:177], v[222:225], v[2:5]
	v_mfma_f32_16x16x32_bf16 v[2:5], v[188:191], v[226:229], v[2:5]
	v_mfma_f32_16x16x32_bf16 v[6:9], v[174:177], v[214:217], v[6:9]
	v_mfma_f32_16x16x32_bf16 v[6:9], v[188:191], v[218:221], v[6:9]
	v_mfma_f32_16x16x32_bf16 v[10:13], v[174:177], v[206:209], v[10:13]
	v_mfma_f32_16x16x32_bf16 v[10:13], v[188:191], v[210:213], v[10:13]
	v_mfma_f32_16x16x32_bf16 v[14:17], v[174:177], v[198:201], v[14:17]
	v_mfma_f32_16x16x32_bf16 v[14:17], v[188:191], v[202:205], v[14:17]
	s_barrier
	s_setprio 0
	s_add_i32 s37, s37, 2
	s_add_u32 s78, s78, 0x100
	s_addc_u32 s79, s79, 0
	s_add_u32 s33, s33, 0x100
	s_addc_u32 s35, s35, 0
	s_cmp_gt_u32 s37, 29
	s_cbranch_scc0 .LBB0_234
	s_and_b64 vcc, exec, s[64:65]
	s_cbranch_vccz .LBB0_237
	s_barrier

; #define PG8_STAGE(bufoff, gbase, voff) do { _Pragma("unroll") for (int _i = 0; _i < 2; ++_i) \
;         __builtin_amdgcn_global_load_lds((const unsigned*)((const char*)(gbase) + (voff)[_i]), (PG8_LAS unsigned*)(lds + (bufoff) + ldsw + _i * 8192), 16, 0, 0); } while (0)
; #define PG8_LDA(dst, b, h) do { _Pragma("unroll") for (int m = 0; m < 4; ++m) _Pragma("unroll") for (int k = 0; k < 2; ++k) dst[m][k] = *(const PG8_LAS bf16x8*)(lds + PG8_SA(b, h) + aoff + m * 2048 + k * 1024); } while (0)
; #define PG8_LDB(dst, b, h) do { _Pragma("unroll") for (int n = 0; n < 2; ++n) _Pragma("unroll") for (int k = 0; k < 2; ++k) dst[n][k] = *(const PG8_LAS bf16x8*)(lds + PG8_SB(b, h) + boff + n * 2048 + k * 1024); } while (0)
; #define PG8_WAIT_L(n) asm volatile("s_waitcnt lgkmcnt(" #n ")" ::: "memory")
; #define PG8_WAIT_V_SEL(sel) asm volatile("s_cmp_eq_u32 %0, 0\n\ts_cbranch_scc1 .Lw8_%=\n\ts_waitcnt vmcnt(22)\n\ts_branch .Lwd_%=\n.Lw8_%=:\n\ts_waitcnt vmcnt(8)\n.Lwd_%=:" :: "s"(sel) : "memory", "scc")
; #define PG8_BAR __builtin_amdgcn_s_barrier()
; #define PG8_SCHED __builtin_amdgcn_sched_barrier(0)
;     ...
;             const bool last = (t == nt * KREP - 2);
;             const int t1w = KREP > 1 ? ((t + 1) & (nt - 1)) : t + 1, t2w = KREP > 1 ? ((t + 2) & (nt - 1)) : t + 2;
;             const char* a1 = cA + (size_t)t1w * kstep;
;             const char* a2 = last ? nA : cA + (size_t)t2w * kstep; const char* b2 = last ? nB : cB + (size_t)t2w * kstep;
;             const char* a3 = a2 + kstep; const char* b3 = b2 + kstep;
;             if (last && has_next) S.a_ready(nxt);
;             const int relax = __builtin_amdgcn_readfirstlane((MK_RELAXW && t == 0 && ui > 0) ? 1 : 0);
;             if constexpr (SP2) {
;             PG8_LDB(B0, 0, 0); PG8_LDB(B1, 0, 1); PG8_SCHED; PG8_LDA(At, 0, 0); PG8_STAGE(PG8_SA(1, 1), a1 + hstep, voffA);
;             PG8_WAIT_V_SEL(relax);
;             PG8_WAIT_L(0); PG8_BAR; PG8_MMA(0, 0, At, B0); PG8_MMA(0, 1, At, B1); PG8_BAR; PG8_SCHED;
;             PG8_LDA(At, 0, 1); PG8_STAGE(PG8_SB(0, 0), b2, voffB); PG8_STAGE(PG8_SB(0, 1), b2 + hstep, voffB); PG8_STAGE(PG8_SA(0, 0), a2, voffA);
;             PG8_WAIT_V_SEL(relax);
;             PG8_WAIT_L(0); PG8_BAR; PG8_MMA(1, 0, At, B0); PG8_MMA(1, 1, At, B1); PG8_BAR; PG8_SCHED;
.LBB0_541:
	s_add_u32 s0, s82, 0xfff80080
	s_addc_u32 s1, s83, -1
	s_add_i32 s79, 0, 0x10000
	s_cmp_eq_u32 s73, 28
	s_cselect_b32 s87, s40, s1
	s_cselect_b32 s86, s41, s0
	s_cselect_b32 s85, s57, s71
	s_cselect_b32 s84, s58, s59
	s_add_i32 s81, 0, 0x14000
	ds_read_b128 v[90:93], v210
	ds_read_b128 v[94:97], v210 offset:1024
	ds_read_b128 v[98:101], v210 offset:2048
	ds_read_b128 v[102:105], v210 offset:3072
	ds_read_b128 v[146:149], v210 offset:16384
	ds_read_b128 v[150:153], v210 offset:17408
	ds_read_b128 v[154:157], v210 offset:18432
	ds_read_b128 v[158:161], v210 offset:19456
	s_add_i32 m0, s44, 0xc000
	ds_read_b128 v[162:165], v230
	ds_read_b128 v[166:169], v230 offset:1024
	ds_read_b128 v[184:187], v230 offset:2048
	ds_read_b128 v[190:193], v230 offset:3072
	ds_read_b128 v[194:197], v230 offset:4096
	ds_read_b128 v[198:201], v230 offset:5120
	ds_read_b128 v[202:205], v230 offset:6144
	ds_read_b128 v[206:209], v230 offset:7168
	global_load_lds_dwordx4 v180, s[82:83]
	s_add_i32 m0, s44, 0xe000
	s_nop 0
	global_load_lds_dwordx4 v188, s[82:83]
	s_waitcnt vmcnt(8)
	s_waitcnt lgkmcnt(0)
	.p2align 3
	s_setprio 1
	s_barrier
	v_mfma_f32_16x16x32_bf16 v[142:145], v[90:93], v[162:165], v[142:145]
	v_mfma_f32_16x16x32_bf16 v[142:145], v[94:97], v[166:169], v[142:145]
	v_mfma_f32_16x16x32_bf16 v[126:129], v[90:93], v[184:187], v[126:129]
	v_mfma_f32_16x16x32_bf16 v[126:129], v[94:97], v[190:193], v[126:129]
	v_mfma_f32_16x16x32_bf16 v[110:113], v[90:93], v[194:197], v[110:113]
	v_mfma_f32_16x16x32_bf16 v[110:113], v[94:97], v[198:201], v[110:113]
	v_mfma_f32_16x16x32_bf16 v[78:81], v[90:93], v[202:205], v[78:81]
	v_mfma_f32_16x16x32_bf16 v[78:81], v[94:97], v[206:209], v[78:81]
	v_mfma_f32_16x16x32_bf16 v[74:77], v[98:101], v[202:205], v[74:77]
	v_mfma_f32_16x16x32_bf16 v[74:77], v[102:105], v[206:209], v[74:77]
	v_mfma_f32_16x16x32_bf16 v[106:109], v[98:101], v[194:197], v[106:109]
	v_mfma_f32_16x16x32_bf16 v[106:109], v[102:105], v[198:201], v[106:109]
	v_mfma_f32_16x16x32_bf16 v[122:125], v[98:101], v[184:187], v[122:125]
	v_mfma_f32_16x16x32_bf16 v[122:125], v[102:105], v[190:193], v[122:125]
	v_mfma_f32_16x16x32_bf16 v[138:141], v[98:101], v[162:165], v[138:141]
	v_mfma_f32_16x16x32_bf16 v[138:141], v[102:105], v[166:169], v[138:141]
	v_mfma_f32_16x16x32_bf16 v[134:137], v[146:149], v[162:165], v[134:137]
	v_mfma_f32_16x16x32_bf16 v[134:137], v[150:153], v[166:169], v[134:137]
	v_mfma_f32_16x16x32_bf16 v[118:121], v[146:149], v[184:187], v[118:121]
	v_mfma_f32_16x16x32_bf16 v[118:121], v[150:153], v[190:193], v[118:121]
	v_mfma_f32_16x16x32_bf16 v[86:89], v[146:149], v[194:197], v[86:89]
	v_mfma_f32_16x16x32_bf16 v[86:89], v[150:153], v[198:201], v[86:89]
	v_mfma_f32_16x16x32_bf16 v[70:73], v[146:149], v[202:205], v[70:73]
	v_mfma_f32_16x16x32_bf16 v[70:73], v[150:153], v[206:209], v[70:73]
	v_mfma_f32_16x16x32_bf16 v[66:69], v[154:157], v[202:205], v[66:69]
	v_mfma_f32_16x16x32_bf16 v[66:69], v[158:161], v[206:209], v[66:69]
	v_mfma_f32_16x16x32_bf16 v[82:85], v[154:157], v[194:197], v[82:85]
	v_mfma_f32_16x16x32_bf16 v[82:85], v[158:161], v[198:201], v[82:85]
	v_mfma_f32_16x16x32_bf16 v[114:117], v[154:157], v[184:187], v[114:117]
	v_mfma_f32_16x16x32_bf16 v[114:117], v[158:161], v[190:193], v[114:117]
	v_mfma_f32_16x16x32_bf16 v[130:133], v[154:157], v[162:165], v[130:133]
	v_mfma_f32_16x16x32_bf16 v[130:133], v[158:161], v[166:169], v[130:133]
	s_barrier
	s_setprio 0
	s_add_i32 s0, s79, s30
	s_mov_b32 m0, s0
	ds_read_b128 v[162:165], v230 offset:16384
	ds_read_b128 v[166:169], v230 offset:17408
	ds_read_b128 v[184:187], v230 offset:18432
	ds_read_b128 v[190:193], v230 offset:19456
	ds_read_b128 v[194:197], v230 offset:20480
	ds_read_b128 v[198:201], v230 offset:21504
	ds_read_b128 v[202:205], v230 offset:22528
	ds_read_b128 v[206:209], v230 offset:23552
	global_load_lds_dwordx4 v182, s[84:85]
	s_add_i32 m0, s0, 0x2000
	s_add_u32 s0, s84, 0x80000
	s_addc_u32 s1, s85, 0
	s_add_i32 s79, s81, s30
	global_load_lds_dwordx4 v178, s[84:85]
	s_mov_b32 m0, s79
	s_nop 0
	global_load_lds_dwordx4 v182, s[0:1]
	s_add_i32 m0, s79, 0x2000
	s_nop 0
	global_load_lds_dwordx4 v178, s[0:1]
	s_mov_b32 m0, s44
	s_nop 0
	global_load_lds_dwordx4 v174, s[86:87]
	s_mov_b32 m0, s45
	s_nop 0
	global_load_lds_dwordx4 v176, s[86:87]
	s_waitcnt vmcnt(8)
	s_waitcnt lgkmcnt(0)
	.p2align 3
	s_setprio 1
	s_barrier
	v_mfma_f32_16x16x32_bf16 v[62:65], v[90:93], v[162:165], v[62:65]
	v_mfma_f32_16x16x32_bf16 v[62:65], v[94:97], v[166:169], v[62:65]
	v_mfma_f32_16x16x32_bf16 v[46:49], v[90:93], v[184:187], v[46:49]
	v_mfma_f32_16x16x32_bf16 v[46:49], v[94:97], v[190:193], v[46:49]
	v_mfma_f32_16x16x32_bf16 v[30:33], v[90:93], v[194:197], v[30:33]
	v_mfma_f32_16x16x32_bf16 v[30:33], v[94:97], v[198:201], v[30:33]
	v_mfma_f32_16x16x32_bf16 v[14:17], v[90:93], v[202:205], v[14:17]
	v_mfma_f32_16x16x32_bf16 v[14:17], v[94:97], v[206:209], v[14:17]
	v_mfma_f32_16x16x32_bf16 v[10:13], v[98:101], v[202:205], v[10:13]
	v_mfma_f32_16x16x32_bf16 v[10:13], v[102:105], v[206:209], v[10:13]
	v_mfma_f32_16x16x32_bf16 v[26:29], v[98:101], v[194:197], v[26:29]
	v_mfma_f32_16x16x32_bf16 v[26:29], v[102:105], v[198:201], v[26:29]
	v_mfma_f32_16x16x32_bf16 v[42:45], v[98:101], v[184:187], v[42:45]
	v_mfma_f32_16x16x32_bf16 v[42:45], v[102:105], v[190:193], v[42:45]
	v_mfma_f32_16x16x32_bf16 v[58:61], v[98:101], v[162:165], v[58:61]
	v_mfma_f32_16x16x32_bf16 v[58:61], v[102:105], v[166:169], v[58:61]
	v_mfma_f32_16x16x32_bf16 v[54:57], v[146:149], v[162:165], v[54:57]
	v_mfma_f32_16x16x32_bf16 v[54:57], v[150:153], v[166:169], v[54:57]
	v_mfma_f32_16x16x32_bf16 v[38:41], v[146:149], v[184:187], v[38:41]
	v_mfma_f32_16x16x32_bf16 v[38:41], v[150:153], v[190:193], v[38:41]
	v_mfma_f32_16x16x32_bf16 v[22:25], v[146:149], v[194:197], v[22:25]
	v_mfma_f32_16x16x32_bf16 v[22:25], v[150:153], v[198:201], v[22:25]
	v_mfma_f32_16x16x32_bf16 v[6:9], v[146:149], v[202:205], v[6:9]
	v_mfma_f32_16x16x32_bf16 v[6:9], v[150:153], v[206:209], v[6:9]
	v_mfma_f32_16x16x32_bf16 v[2:5], v[154:157], v[202:205], v[2:5]
	v_mfma_f32_16x16x32_bf16 v[2:5], v[158:161], v[206:209], v[2:5]
	v_mfma_f32_16x16x32_bf16 v[18:21], v[154:157], v[194:197], v[18:21]
	v_mfma_f32_16x16x32_bf16 v[18:21], v[158:161], v[198:201], v[18:21]
	v_mfma_f32_16x16x32_bf16 v[34:37], v[154:157], v[184:187], v[34:37]
	v_mfma_f32_16x16x32_bf16 v[34:37], v[158:161], v[190:193], v[34:37]
	v_mfma_f32_16x16x32_bf16 v[50:53], v[154:157], v[162:165], v[50:53]
	v_mfma_f32_16x16x32_bf16 v[50:53], v[158:161], v[166:169], v[50:53]
	s_barrier
; #define PG8_STAGE(bufoff, gbase, voff) do { _Pragma("unroll") for (int _i = 0; _i < 2; ++_i) \
;         __builtin_amdgcn_global_load_lds((const unsigned*)((const char*)(gbase) + (voff)[_i]), (PG8_LAS unsigned*)(lds + (bufoff) + ldsw + _i * 8192), 16, 0, 0); } while (0)
; #define PG8_LDA(dst, b, h) do { _Pragma("unroll") for (int m = 0; m < 4; ++m) _Pragma("unroll") for (int k = 0; k < 2; ++k) dst[m][k] = *(const PG8_LAS bf16x8*)(lds + PG8_SA(b, h) + aoff + m * 2048 + k * 1024); } while (0)
; #define PG8_LDB(dst, b, h) do { _Pragma("unroll") for (int n = 0; n < 2; ++n) _Pragma("unroll") for (int k = 0; k < 2; ++k) dst[n][k] = *(const PG8_LAS bf16x8*)(lds + PG8_SB(b, h) + boff + n * 2048 + k * 1024); } while (0)
; #define PG8_WAIT_V(n) asm volatile("s_waitcnt vmcnt(" #n ")" ::: "memory")
; #define PG8_WAIT_L(n) asm volatile("s_waitcnt lgkmcnt(" #n ")" ::: "memory")
; #define PG8_BAR __builtin_amdgcn_s_barrier()
; #define PG8_SCHED __builtin_amdgcn_sched_barrier(0)
;     ...
;             PG8_WAIT_L(0); PG8_BAR; PG8_MMA(1, 0, At, B0); PG8_MMA(1, 1, At, B1); PG8_BAR; PG8_SCHED;
;             PG8_LDB(B0, 1, 0); PG8_LDB(B1, 1, 1); PG8_SCHED; PG8_LDA(At, 1, 0); PG8_STAGE(PG8_SA(0, 1), a2 + hstep, voffA);
;             PG8_WAIT_V(8); PG8_WAIT_L(0); PG8_BAR; PG8_MMA(0, 0, At, B0); PG8_MMA(0, 1, At, B1); PG8_BAR; PG8_SCHED;
;             PG8_LDA(At, 1, 1); PG8_STAGE(PG8_SB(1, 0), b3, voffB); PG8_STAGE(PG8_SB(1, 1), b3 + hstep, voffB); PG8_STAGE(PG8_SA(1, 0), a3, voffA);
;             PG8_WAIT_V(8); PG8_WAIT_L(0); PG8_BAR; PG8_MMA(1, 0, At, B0); PG8_MMA(1, 1, At, B1); PG8_BAR; PG8_SCHED;
	s_setprio 0
	s_add_i32 s79, 0, 0x18000
	s_add_i32 s81, 0, 0x1c000
	ds_read_b128 v[90:93], v210 offset:32768
	ds_read_b128 v[94:97], v210 offset:33792
	ds_read_b128 v[98:101], v210 offset:34816
	ds_read_b128 v[102:105], v210 offset:35840
	ds_read_b128 v[146:149], v210 offset:49152
	ds_read_b128 v[150:153], v210 offset:50176
	ds_read_b128 v[154:157], v210 offset:51200
	ds_read_b128 v[158:161], v210 offset:52224
	s_add_u32 s0, s86, 0x80000
	s_addc_u32 s1, s87, 0
	s_mov_b32 m0, s46
	ds_read_b128 v[162:165], v230 offset:32768
	ds_read_b128 v[166:169], v230 offset:33792
	ds_read_b128 v[184:187], v230 offset:34816
	ds_read_b128 v[190:193], v230 offset:35840
	ds_read_b128 v[194:197], v230 offset:36864
	ds_read_b128 v[198:201], v230 offset:37888
	ds_read_b128 v[202:205], v230 offset:38912
	ds_read_b128 v[206:209], v230 offset:39936
	global_load_lds_dwordx4 v174, s[0:1]
	s_mov_b32 m0, s47
	s_nop 0
	global_load_lds_dwordx4 v176, s[0:1]
	s_waitcnt vmcnt(8)
	s_waitcnt lgkmcnt(0)
	.p2align 3
	s_setprio 1
	s_barrier
	v_mfma_f32_16x16x32_bf16 v[142:145], v[90:93], v[162:165], v[142:145]
	v_mfma_f32_16x16x32_bf16 v[142:145], v[94:97], v[166:169], v[142:145]
	v_mfma_f32_16x16x32_bf16 v[126:129], v[90:93], v[184:187], v[126:129]
	v_mfma_f32_16x16x32_bf16 v[126:129], v[94:97], v[190:193], v[126:129]
	v_mfma_f32_16x16x32_bf16 v[110:113], v[90:93], v[194:197], v[110:113]
	v_mfma_f32_16x16x32_bf16 v[110:113], v[94:97], v[198:201], v[110:113]
	v_mfma_f32_16x16x32_bf16 v[78:81], v[90:93], v[202:205], v[78:81]
	v_mfma_f32_16x16x32_bf16 v[78:81], v[94:97], v[206:209], v[78:81]
	v_mfma_f32_16x16x32_bf16 v[74:77], v[98:101], v[202:205], v[74:77]
	v_mfma_f32_16x16x32_bf16 v[74:77], v[102:105], v[206:209], v[74:77]
	v_mfma_f32_16x16x32_bf16 v[106:109], v[98:101], v[194:197], v[106:109]
	v_mfma_f32_16x16x32_bf16 v[106:109], v[102:105], v[198:201], v[106:109]
	v_mfma_f32_16x16x32_bf16 v[122:125], v[98:101], v[184:187], v[122:125]
	v_mfma_f32_16x16x32_bf16 v[122:125], v[102:105], v[190:193], v[122:125]
	v_mfma_f32_16x16x32_bf16 v[138:141], v[98:101], v[162:165], v[138:141]
	v_mfma_f32_16x16x32_bf16 v[138:141], v[102:105], v[166:169], v[138:141]
	v_mfma_f32_16x16x32_bf16 v[134:137], v[146:149], v[162:165], v[134:137]
	v_mfma_f32_16x16x32_bf16 v[134:137], v[150:153], v[166:169], v[134:137]
	v_mfma_f32_16x16x32_bf16 v[118:121], v[146:149], v[184:187], v[118:121]
	v_mfma_f32_16x16x32_bf16 v[118:121], v[150:153], v[190:193], v[118:121]
	v_mfma_f32_16x16x32_bf16 v[86:89], v[146:149], v[194:197], v[86:89]
	v_mfma_f32_16x16x32_bf16 v[86:89], v[150:153], v[198:201], v[86:89]
	v_mfma_f32_16x16x32_bf16 v[70:73], v[146:149], v[202:205], v[70:73]
	v_mfma_f32_16x16x32_bf16 v[70:73], v[150:153], v[206:209], v[70:73]
	v_mfma_f32_16x16x32_bf16 v[66:69], v[154:157], v[202:205], v[66:69]
	v_mfma_f32_16x16x32_bf16 v[66:69], v[158:161], v[206:209], v[66:69]
	v_mfma_f32_16x16x32_bf16 v[82:85], v[154:157], v[194:197], v[82:85]
	v_mfma_f32_16x16x32_bf16 v[82:85], v[158:161], v[198:201], v[82:85]
	v_mfma_f32_16x16x32_bf16 v[114:117], v[154:157], v[184:187], v[114:117]
	v_mfma_f32_16x16x32_bf16 v[114:117], v[158:161], v[190:193], v[114:117]
	v_mfma_f32_16x16x32_bf16 v[130:133], v[154:157], v[162:165], v[130:133]
	v_mfma_f32_16x16x32_bf16 v[130:133], v[158:161], v[166:169], v[130:133]
	s_barrier
	s_setprio 0
	s_add_i32 s0, s79, s30
	s_mov_b32 m0, s0
	ds_read_b128 v[162:165], v230 offset:49152
	ds_read_b128 v[166:169], v230 offset:50176
	ds_read_b128 v[184:187], v230 offset:51200
	ds_read_b128 v[190:193], v230 offset:52224
	ds_read_b128 v[194:197], v230 offset:53248
	ds_read_b128 v[198:201], v230 offset:54272
	ds_read_b128 v[202:205], v230 offset:55296
	ds_read_b128 v[206:209], v230 offset:56320
	s_add_u32 s100, s84, 0x80
	s_addc_u32 s101, s85, 0
	global_load_lds_dwordx4 v182, s[100:101]
	s_add_i32 m0, s0, 0x2000
	s_add_u32 s0, s84, 0x80080
	s_addc_u32 s1, s85, 0
	s_add_i32 s79, s81, s30
	global_load_lds_dwordx4 v178, s[100:101]
	s_mov_b32 m0, s79
	s_nop 0
	global_load_lds_dwordx4 v182, s[0:1]
	s_add_i32 m0, s79, 0x2000
	s_nop 0
	global_load_lds_dwordx4 v178, s[0:1]
	s_mov_b32 m0, s49
	s_nop 0
	s_add_u32 s100, s86, 0x80
	s_addc_u32 s101, s87, 0
	global_load_lds_dwordx4 v174, s[100:101]
	s_mov_b32 m0, s50
	s_nop 0
	global_load_lds_dwordx4 v176, s[100:101]
	s_waitcnt vmcnt(8)
	s_waitcnt lgkmcnt(0)
	.p2align 3
	s_setprio 1
	s_barrier
	v_mfma_f32_16x16x32_bf16 v[62:65], v[90:93], v[162:165], v[62:65]
	v_mfma_f32_16x16x32_bf16 v[62:65], v[94:97], v[166:169], v[62:65]
	v_mfma_f32_16x16x32_bf16 v[46:49], v[90:93], v[184:187], v[46:49]
	v_mfma_f32_16x16x32_bf16 v[46:49], v[94:97], v[190:193], v[46:49]
	v_mfma_f32_16x16x32_bf16 v[30:33], v[90:93], v[194:197], v[30:33]
	v_mfma_f32_16x16x32_bf16 v[30:33], v[94:97], v[198:201], v[30:33]
	v_mfma_f32_16x16x32_bf16 v[14:17], v[90:93], v[202:205], v[14:17]
	v_mfma_f32_16x16x32_bf16 v[14:17], v[94:97], v[206:209], v[14:17]
	v_mfma_f32_16x16x32_bf16 v[10:13], v[98:101], v[202:205], v[10:13]
	v_mfma_f32_16x16x32_bf16 v[10:13], v[102:105], v[206:209], v[10:13]
	v_mfma_f32_16x16x32_bf16 v[26:29], v[98:101], v[194:197], v[26:29]
	v_mfma_f32_16x16x32_bf16 v[26:29], v[102:105], v[198:201], v[26:29]
	v_mfma_f32_16x16x32_bf16 v[42:45], v[98:101], v[184:187], v[42:45]
	v_mfma_f32_16x16x32_bf16 v[42:45], v[102:105], v[190:193], v[42:45]
	v_mfma_f32_16x16x32_bf16 v[58:61], v[98:101], v[162:165], v[58:61]
	v_mfma_f32_16x16x32_bf16 v[58:61], v[102:105], v[166:169], v[58:61]
	v_mfma_f32_16x16x32_bf16 v[54:57], v[146:149], v[162:165], v[54:57]
	v_mfma_f32_16x16x32_bf16 v[54:57], v[150:153], v[166:169], v[54:57]
	v_mfma_f32_16x16x32_bf16 v[38:41], v[146:149], v[184:187], v[38:41]
	v_mfma_f32_16x16x32_bf16 v[38:41], v[150:153], v[190:193], v[38:41]
	v_mfma_f32_16x16x32_bf16 v[22:25], v[146:149], v[194:197], v[22:25]
	v_mfma_f32_16x16x32_bf16 v[22:25], v[150:153], v[198:201], v[22:25]
	v_mfma_f32_16x16x32_bf16 v[6:9], v[146:149], v[202:205], v[6:9]
	v_mfma_f32_16x16x32_bf16 v[6:9], v[150:153], v[206:209], v[6:9]
	v_mfma_f32_16x16x32_bf16 v[2:5], v[154:157], v[202:205], v[2:5]
	v_mfma_f32_16x16x32_bf16 v[2:5], v[158:161], v[206:209], v[2:5]
	v_mfma_f32_16x16x32_bf16 v[18:21], v[154:157], v[194:197], v[18:21]
	v_mfma_f32_16x16x32_bf16 v[18:21], v[158:161], v[198:201], v[18:21]
	v_mfma_f32_16x16x32_bf16 v[34:37], v[154:157], v[184:187], v[34:37]
	v_mfma_f32_16x16x32_bf16 v[34:37], v[158:161], v[190:193], v[34:37]
	v_mfma_f32_16x16x32_bf16 v[50:53], v[154:157], v[162:165], v[50:53]
	v_mfma_f32_16x16x32_bf16 v[50:53], v[158:161], v[166:169], v[50:53]
	s_barrier
	s_setprio 0
	s_add_i32 s73, s73, 2
	s_add_u32 s82, s82, 0x100
	s_addc_u32 s83, s83, 0
	s_add_u32 s59, s59, 0x100
	s_addc_u32 s71, s71, 0
	s_cmp_gt_u32 s73, 29
	s_cbranch_scc0 .LBB0_541
	s_and_b64 vcc, exec, s[68:69]
	s_cbranch_vccz .LBB0_544
	s_barrier

; #define PG8_STAGE(bufoff, gbase, voff) do { _Pragma("unroll") for (int _i = 0; _i < 2; ++_i) \
;         __builtin_amdgcn_global_load_lds((const unsigned*)((const char*)(gbase) + (voff)[_i]), (PG8_LAS unsigned*)(lds + (bufoff) + ldsw + _i * 8192), 16, 0, 0); } while (0)
; #define PG8_LDA(dst, b, h) do { _Pragma("unroll") for (int m = 0; m < 4; ++m) _Pragma("unroll") for (int k = 0; k < 2; ++k) dst[m][k] = *(const PG8_LAS bf16x8*)(lds + PG8_SA(b, h) + aoff + m * 2048 + k * 1024); } while (0)
; #define PG8_LDB(dst, b, h) do { _Pragma("unroll") for (int n = 0; n < 2; ++n) _Pragma("unroll") for (int k = 0; k < 2; ++k) dst[n][k] = *(const PG8_LAS bf16x8*)(lds + PG8_SB(b, h) + boff + n * 2048 + k * 1024); } while (0)
; #define PG8_WAIT_L(n) asm volatile("s_waitcnt lgkmcnt(" #n ")" ::: "memory")
; #define PG8_WAIT_V_SEL(sel) asm volatile("s_cmp_eq_u32 %0, 0\n\ts_cbranch_scc1 .Lw8_%=\n\ts_waitcnt vmcnt(22)\n\ts_branch .Lwd_%=\n.Lw8_%=:\n\ts_waitcnt vmcnt(8)\n.Lwd_%=:" :: "s"(sel) : "memory", "scc")
; #define PG8_BAR __builtin_amdgcn_s_barrier()
; #define PG8_SCHED __builtin_amdgcn_sched_barrier(0)
;     ...
;             const bool last = (t == nt * KREP - 2);
;             const int t1w = KREP > 1 ? ((t + 1) & (nt - 1)) : t + 1, t2w = KREP > 1 ? ((t + 2) & (nt - 1)) : t + 2;
;             const char* a1 = cA + (size_t)t1w * kstep;
;             const char* a2 = last ? nA : cA + (size_t)t2w * kstep; const char* b2 = last ? nB : cB + (size_t)t2w * kstep;
;             const char* a3 = a2 + kstep; const char* b3 = b2 + kstep;
;             if (last && has_next) S.a_ready(nxt);
;             const int relax = __builtin_amdgcn_readfirstlane((MK_RELAXW && t == 0 && ui > 0) ? 1 : 0);
;             if constexpr (SP2) {
;             PG8_LDB(B0, 0, 0); PG8_LDB(B1, 0, 1); PG8_SCHED; PG8_LDA(At, 0, 0); PG8_STAGE(PG8_SA(1, 1), a1 + hstep, voffA);
;             PG8_WAIT_V_SEL(relax);
;             PG8_WAIT_L(0); PG8_BAR; PG8_MMA(0, 0, At, B0); PG8_MMA(0, 1, At, B1); PG8_BAR; PG8_SCHED;
;             PG8_LDA(At, 0, 1); PG8_STAGE(PG8_SB(0, 0), b2, voffB); PG8_STAGE(PG8_SB(0, 1), b2 + hstep, voffB); PG8_STAGE(PG8_SA(0, 0), a2, voffA);
;             PG8_WAIT_V_SEL(relax);
;             PG8_WAIT_L(0); PG8_BAR; PG8_MMA(1, 0, At, B0); PG8_MMA(1, 1, At, B1); PG8_BAR; PG8_SCHED;
.LBB0_596:
	s_add_u32 s0, s74, 0xfff80080
	s_addc_u32 s1, s75, -1
	s_add_i32 s83, 0, 0x10000
	s_cmp_eq_u32 s82, 28
	s_cselect_b32 s79, s40, s1
	s_cselect_b32 s78, s41, s0
	s_cselect_b32 s77, s65, s81
	s_cselect_b32 s76, s73, s80
	s_add_i32 s84, 0, 0x14000
	ds_read_b128 v[150:153], v180
	ds_read_b128 v[154:157], v180 offset:1024
	ds_read_b128 v[158:161], v180 offset:2048
	ds_read_b128 v[162:165], v180 offset:3072
	ds_read_b128 v[166:169], v180 offset:16384
	ds_read_b128 v[172:175], v180 offset:17408
	ds_read_b128 v[176:179], v180 offset:18432
	ds_read_b128 v[188:191], v180 offset:19456
	s_add_i32 m0, s35, 0xc000
	ds_read_b128 v[192:195], v148
	ds_read_b128 v[196:199], v148 offset:1024
	ds_read_b128 v[200:203], v148 offset:2048
	ds_read_b128 v[204:207], v148 offset:3072
	ds_read_b128 v[208:211], v148 offset:4096
	ds_read_b128 v[212:215], v148 offset:5120
	ds_read_b128 v[216:219], v148 offset:6144
	ds_read_b128 v[220:223], v148 offset:7168
	global_load_lds_dwordx4 v140, s[74:75]
	s_add_i32 m0, s35, 0xe000
	s_nop 0
	global_load_lds_dwordx4 v142, s[74:75]
	s_waitcnt vmcnt(8)
	s_waitcnt lgkmcnt(0)
	.p2align 3
	s_setprio 1
	s_barrier
	v_mfma_f32_16x16x32_bf16 v[126:129], v[150:153], v[192:195], v[126:129]
	v_mfma_f32_16x16x32_bf16 v[126:129], v[154:157], v[196:199], v[126:129]
	v_mfma_f32_16x16x32_bf16 v[122:125], v[150:153], v[200:203], v[122:125]
	v_mfma_f32_16x16x32_bf16 v[122:125], v[154:157], v[204:207], v[122:125]
	v_mfma_f32_16x16x32_bf16 v[118:121], v[150:153], v[208:211], v[118:121]
	v_mfma_f32_16x16x32_bf16 v[118:121], v[154:157], v[212:215], v[118:121]
	v_mfma_f32_16x16x32_bf16 v[114:117], v[150:153], v[216:219], v[114:117]
	v_mfma_f32_16x16x32_bf16 v[114:117], v[154:157], v[220:223], v[114:117]
	v_mfma_f32_16x16x32_bf16 v[98:101], v[158:161], v[216:219], v[98:101]
	v_mfma_f32_16x16x32_bf16 v[98:101], v[162:165], v[220:223], v[98:101]
	v_mfma_f32_16x16x32_bf16 v[102:105], v[158:161], v[208:211], v[102:105]
	v_mfma_f32_16x16x32_bf16 v[102:105], v[162:165], v[212:215], v[102:105]
	v_mfma_f32_16x16x32_bf16 v[106:109], v[158:161], v[200:203], v[106:109]
	v_mfma_f32_16x16x32_bf16 v[106:109], v[162:165], v[204:207], v[106:109]
	v_mfma_f32_16x16x32_bf16 v[110:113], v[158:161], v[192:195], v[110:113]
	v_mfma_f32_16x16x32_bf16 v[110:113], v[162:165], v[196:199], v[110:113]
	v_mfma_f32_16x16x32_bf16 v[70:73], v[166:169], v[192:195], v[70:73]
	v_mfma_f32_16x16x32_bf16 v[70:73], v[172:175], v[196:199], v[70:73]
	v_mfma_f32_16x16x32_bf16 v[66:69], v[166:169], v[200:203], v[66:69]
	v_mfma_f32_16x16x32_bf16 v[66:69], v[172:175], v[204:207], v[66:69]
	v_mfma_f32_16x16x32_bf16 v[58:61], v[166:169], v[208:211], v[58:61]
	v_mfma_f32_16x16x32_bf16 v[58:61], v[172:175], v[212:215], v[58:61]
	v_mfma_f32_16x16x32_bf16 v[46:49], v[166:169], v[216:219], v[46:49]
	v_mfma_f32_16x16x32_bf16 v[46:49], v[172:175], v[220:223], v[46:49]
	v_mfma_f32_16x16x32_bf16 v[34:37], v[176:179], v[216:219], v[34:37]
	v_mfma_f32_16x16x32_bf16 v[34:37], v[188:191], v[220:223], v[34:37]
	v_mfma_f32_16x16x32_bf16 v[38:41], v[176:179], v[208:211], v[38:41]
	v_mfma_f32_16x16x32_bf16 v[38:41], v[188:191], v[212:215], v[38:41]
	v_mfma_f32_16x16x32_bf16 v[42:45], v[176:179], v[200:203], v[42:45]
	v_mfma_f32_16x16x32_bf16 v[42:45], v[188:191], v[204:207], v[42:45]
	v_mfma_f32_16x16x32_bf16 v[50:53], v[176:179], v[192:195], v[50:53]
	v_mfma_f32_16x16x32_bf16 v[50:53], v[188:191], v[196:199], v[50:53]
	s_barrier
	s_setprio 0
	s_add_i32 s0, s83, s20
	s_mov_b32 m0, s0
	ds_read_b128 v[192:195], v148 offset:16384
	ds_read_b128 v[196:199], v148 offset:17408
	ds_read_b128 v[200:203], v148 offset:18432
	ds_read_b128 v[204:207], v148 offset:19456
	ds_read_b128 v[208:211], v148 offset:20480
	ds_read_b128 v[212:215], v148 offset:21504
	ds_read_b128 v[216:219], v148 offset:22528
	ds_read_b128 v[220:223], v148 offset:23552
	global_load_lds_dwordx4 v132, s[76:77]
	s_add_i32 m0, s0, 0x2000
	s_add_u32 s0, s76, 0x80000
	s_addc_u32 s1, s77, 0
	s_add_i32 s83, s84, s20
	global_load_lds_dwordx4 v136, s[76:77]
	s_mov_b32 m0, s83
	s_nop 0
	global_load_lds_dwordx4 v132, s[0:1]
	s_add_i32 m0, s83, 0x2000
	s_nop 0
	global_load_lds_dwordx4 v136, s[0:1]
	s_mov_b32 m0, s35
	s_nop 0
	global_load_lds_dwordx4 v130, s[78:79]
	s_mov_b32 m0, s37
	s_nop 0
	global_load_lds_dwordx4 v134, s[78:79]
	s_waitcnt vmcnt(8)
	s_waitcnt lgkmcnt(0)
	.p2align 3
	s_setprio 1
	s_barrier
	v_mfma_f32_16x16x32_bf16 v[94:97], v[150:153], v[192:195], v[94:97]
	v_mfma_f32_16x16x32_bf16 v[94:97], v[154:157], v[196:199], v[94:97]
	v_mfma_f32_16x16x32_bf16 v[90:93], v[150:153], v[200:203], v[90:93]
	v_mfma_f32_16x16x32_bf16 v[90:93], v[154:157], v[204:207], v[90:93]
	v_mfma_f32_16x16x32_bf16 v[86:89], v[150:153], v[208:211], v[86:89]
	v_mfma_f32_16x16x32_bf16 v[86:89], v[154:157], v[212:215], v[86:89]
	v_mfma_f32_16x16x32_bf16 v[82:85], v[150:153], v[216:219], v[82:85]
	v_mfma_f32_16x16x32_bf16 v[82:85], v[154:157], v[220:223], v[82:85]
	v_mfma_f32_16x16x32_bf16 v[54:57], v[158:161], v[216:219], v[54:57]
	v_mfma_f32_16x16x32_bf16 v[54:57], v[162:165], v[220:223], v[54:57]
	v_mfma_f32_16x16x32_bf16 v[62:65], v[158:161], v[208:211], v[62:65]
	v_mfma_f32_16x16x32_bf16 v[62:65], v[162:165], v[212:215], v[62:65]
	v_mfma_f32_16x16x32_bf16 v[74:77], v[158:161], v[200:203], v[74:77]
	v_mfma_f32_16x16x32_bf16 v[74:77], v[162:165], v[204:207], v[74:77]
	v_mfma_f32_16x16x32_bf16 v[78:81], v[158:161], v[192:195], v[78:81]
	v_mfma_f32_16x16x32_bf16 v[78:81], v[162:165], v[196:199], v[78:81]
	v_mfma_f32_16x16x32_bf16 v[30:33], v[166:169], v[192:195], v[30:33]
	v_mfma_f32_16x16x32_bf16 v[30:33], v[172:175], v[196:199], v[30:33]
	v_mfma_f32_16x16x32_bf16 v[26:29], v[166:169], v[200:203], v[26:29]
	v_mfma_f32_16x16x32_bf16 v[26:29], v[172:175], v[204:207], v[26:29]
	v_mfma_f32_16x16x32_bf16 v[22:25], v[166:169], v[208:211], v[22:25]
	v_mfma_f32_16x16x32_bf16 v[22:25], v[172:175], v[212:215], v[22:25]
	v_mfma_f32_16x16x32_bf16 v[18:21], v[166:169], v[216:219], v[18:21]
	v_mfma_f32_16x16x32_bf16 v[18:21], v[172:175], v[220:223], v[18:21]
	v_mfma_f32_16x16x32_bf16 v[2:5], v[176:179], v[216:219], v[2:5]
	v_mfma_f32_16x16x32_bf16 v[2:5], v[188:191], v[220:223], v[2:5]
	v_mfma_f32_16x16x32_bf16 v[6:9], v[176:179], v[208:211], v[6:9]
	v_mfma_f32_16x16x32_bf16 v[6:9], v[188:191], v[212:215], v[6:9]
	v_mfma_f32_16x16x32_bf16 v[10:13], v[176:179], v[200:203], v[10:13]
	v_mfma_f32_16x16x32_bf16 v[10:13], v[188:191], v[204:207], v[10:13]
	v_mfma_f32_16x16x32_bf16 v[14:17], v[176:179], v[192:195], v[14:17]
	v_mfma_f32_16x16x32_bf16 v[14:17], v[188:191], v[196:199], v[14:17]
	s_barrier
; #define PG8_STAGE(bufoff, gbase, voff) do { _Pragma("unroll") for (int _i = 0; _i < 2; ++_i) \
;         __builtin_amdgcn_global_load_lds((const unsigned*)((const char*)(gbase) + (voff)[_i]), (PG8_LAS unsigned*)(lds + (bufoff) + ldsw + _i * 8192), 16, 0, 0); } while (0)
; #define PG8_LDA(dst, b, h) do { _Pragma("unroll") for (int m = 0; m < 4; ++m) _Pragma("unroll") for (int k = 0; k < 2; ++k) dst[m][k] = *(const PG8_LAS bf16x8*)(lds + PG8_SA(b, h) + aoff + m * 2048 + k * 1024); } while (0)
; #define PG8_LDB(dst, b, h) do { _Pragma("unroll") for (int n = 0; n < 2; ++n) _Pragma("unroll") for (int k = 0; k < 2; ++k) dst[n][k] = *(const PG8_LAS bf16x8*)(lds + PG8_SB(b, h) + boff + n * 2048 + k * 1024); } while (0)
; #define PG8_WAIT_V(n) asm volatile("s_waitcnt vmcnt(" #n ")" ::: "memory")
; #define PG8_WAIT_L(n) asm volatile("s_waitcnt lgkmcnt(" #n ")" ::: "memory")
; #define PG8_BAR __builtin_amdgcn_s_barrier()
; #define PG8_SCHED __builtin_amdgcn_sched_barrier(0)
;     ...
;             PG8_WAIT_L(0); PG8_BAR; PG8_MMA(1, 0, At, B0); PG8_MMA(1, 1, At, B1); PG8_BAR; PG8_SCHED;
;             PG8_LDB(B0, 1, 0); PG8_LDB(B1, 1, 1); PG8_SCHED; PG8_LDA(At, 1, 0); PG8_STAGE(PG8_SA(0, 1), a2 + hstep, voffA);
;             PG8_WAIT_V(8); PG8_WAIT_L(0); PG8_BAR; PG8_MMA(0, 0, At, B0); PG8_MMA(0, 1, At, B1); PG8_BAR; PG8_SCHED;
;             PG8_LDA(At, 1, 1); PG8_STAGE(PG8_SB(1, 0), b3, voffB); PG8_STAGE(PG8_SB(1, 1), b3 + hstep, voffB); PG8_STAGE(PG8_SA(1, 0), a3, voffA);
;             PG8_WAIT_V(8); PG8_WAIT_L(0); PG8_BAR; PG8_MMA(1, 0, At, B0); PG8_MMA(1, 1, At, B1); PG8_BAR; PG8_SCHED;
	s_setprio 0
	s_add_i32 s83, 0, 0x18000
	s_add_i32 s84, 0, 0x1c000
	ds_read_b128 v[150:153], v180 offset:32768
	ds_read_b128 v[154:157], v180 offset:33792
	ds_read_b128 v[158:161], v180 offset:34816
	ds_read_b128 v[162:165], v180 offset:35840
	ds_read_b128 v[166:169], v180 offset:49152
	ds_read_b128 v[172:175], v180 offset:50176
	ds_read_b128 v[176:179], v180 offset:51200
	ds_read_b128 v[188:191], v180 offset:52224
	s_add_u32 s0, s78, 0x80000
	s_addc_u32 s1, s79, 0
	s_mov_b32 m0, s43
	ds_read_b128 v[192:195], v148 offset:32768
	ds_read_b128 v[196:199], v148 offset:33792
	ds_read_b128 v[200:203], v148 offset:34816
	ds_read_b128 v[204:207], v148 offset:35840
	ds_read_b128 v[208:211], v148 offset:36864
	ds_read_b128 v[212:215], v148 offset:37888
	ds_read_b128 v[216:219], v148 offset:38912
	ds_read_b128 v[220:223], v148 offset:39936
	global_load_lds_dwordx4 v130, s[0:1]
	s_mov_b32 m0, s44
	s_nop 0
	global_load_lds_dwordx4 v134, s[0:1]
	s_waitcnt vmcnt(8)
	s_waitcnt lgkmcnt(0)
	.p2align 3
	s_setprio 1
	s_barrier
	v_mfma_f32_16x16x32_bf16 v[126:129], v[150:153], v[192:195], v[126:129]
	v_mfma_f32_16x16x32_bf16 v[126:129], v[154:157], v[196:199], v[126:129]
	v_mfma_f32_16x16x32_bf16 v[122:125], v[150:153], v[200:203], v[122:125]
	v_mfma_f32_16x16x32_bf16 v[122:125], v[154:157], v[204:207], v[122:125]
	v_mfma_f32_16x16x32_bf16 v[118:121], v[150:153], v[208:211], v[118:121]
	v_mfma_f32_16x16x32_bf16 v[118:121], v[154:157], v[212:215], v[118:121]
	v_mfma_f32_16x16x32_bf16 v[114:117], v[150:153], v[216:219], v[114:117]
	v_mfma_f32_16x16x32_bf16 v[114:117], v[154:157], v[220:223], v[114:117]
	v_mfma_f32_16x16x32_bf16 v[98:101], v[158:161], v[216:219], v[98:101]
	v_mfma_f32_16x16x32_bf16 v[98:101], v[162:165], v[220:223], v[98:101]
	v_mfma_f32_16x16x32_bf16 v[102:105], v[158:161], v[208:211], v[102:105]
	v_mfma_f32_16x16x32_bf16 v[102:105], v[162:165], v[212:215], v[102:105]
	v_mfma_f32_16x16x32_bf16 v[106:109], v[158:161], v[200:203], v[106:109]
	v_mfma_f32_16x16x32_bf16 v[106:109], v[162:165], v[204:207], v[106:109]
	v_mfma_f32_16x16x32_bf16 v[110:113], v[158:161], v[192:195], v[110:113]
	v_mfma_f32_16x16x32_bf16 v[110:113], v[162:165], v[196:199], v[110:113]
	v_mfma_f32_16x16x32_bf16 v[70:73], v[166:169], v[192:195], v[70:73]
	v_mfma_f32_16x16x32_bf16 v[70:73], v[172:175], v[196:199], v[70:73]
	v_mfma_f32_16x16x32_bf16 v[66:69], v[166:169], v[200:203], v[66:69]
	v_mfma_f32_16x16x32_bf16 v[66:69], v[172:175], v[204:207], v[66:69]
	v_mfma_f32_16x16x32_bf16 v[58:61], v[166:169], v[208:211], v[58:61]
	v_mfma_f32_16x16x32_bf16 v[58:61], v[172:175], v[212:215], v[58:61]
	v_mfma_f32_16x16x32_bf16 v[46:49], v[166:169], v[216:219], v[46:49]
	v_mfma_f32_16x16x32_bf16 v[46:49], v[172:175], v[220:223], v[46:49]
	v_mfma_f32_16x16x32_bf16 v[34:37], v[176:179], v[216:219], v[34:37]
	v_mfma_f32_16x16x32_bf16 v[34:37], v[188:191], v[220:223], v[34:37]
	v_mfma_f32_16x16x32_bf16 v[38:41], v[176:179], v[208:211], v[38:41]
	v_mfma_f32_16x16x32_bf16 v[38:41], v[188:191], v[212:215], v[38:41]
	v_mfma_f32_16x16x32_bf16 v[42:45], v[176:179], v[200:203], v[42:45]
	v_mfma_f32_16x16x32_bf16 v[42:45], v[188:191], v[204:207], v[42:45]
	v_mfma_f32_16x16x32_bf16 v[50:53], v[176:179], v[192:195], v[50:53]
	v_mfma_f32_16x16x32_bf16 v[50:53], v[188:191], v[196:199], v[50:53]
	s_barrier
	s_setprio 0
	s_add_i32 s0, s83, s20
	s_mov_b32 m0, s0
	ds_read_b128 v[192:195], v148 offset:49152
	ds_read_b128 v[196:199], v148 offset:50176
	ds_read_b128 v[200:203], v148 offset:51200
	ds_read_b128 v[204:207], v148 offset:52224
	ds_read_b128 v[208:211], v148 offset:53248
	ds_read_b128 v[212:215], v148 offset:54272
	ds_read_b128 v[216:219], v148 offset:55296
	ds_read_b128 v[220:223], v148 offset:56320
	s_add_u32 s100, s76, 0x80
	s_addc_u32 s101, s77, 0
	global_load_lds_dwordx4 v132, s[100:101]
	s_add_i32 m0, s0, 0x2000
	s_add_u32 s0, s76, 0x80080
	s_addc_u32 s1, s77, 0
	s_add_i32 s76, s84, s20
	global_load_lds_dwordx4 v136, s[100:101]
	s_mov_b32 m0, s76
	s_nop 0
	global_load_lds_dwordx4 v132, s[0:1]
	s_add_i32 m0, s76, 0x2000
	s_nop 0
	global_load_lds_dwordx4 v136, s[0:1]
	s_mov_b32 m0, s48
	s_nop 0
	s_add_u32 s100, s78, 0x80
	s_addc_u32 s101, s79, 0
	global_load_lds_dwordx4 v130, s[100:101]
	s_mov_b32 m0, s49
	s_nop 0
	global_load_lds_dwordx4 v134, s[100:101]
	s_waitcnt vmcnt(8)
	s_waitcnt lgkmcnt(0)
	.p2align 3
	s_setprio 1
	s_barrier
	v_mfma_f32_16x16x32_bf16 v[94:97], v[150:153], v[192:195], v[94:97]
	v_mfma_f32_16x16x32_bf16 v[94:97], v[154:157], v[196:199], v[94:97]
	v_mfma_f32_16x16x32_bf16 v[90:93], v[150:153], v[200:203], v[90:93]
	v_mfma_f32_16x16x32_bf16 v[90:93], v[154:157], v[204:207], v[90:93]
	v_mfma_f32_16x16x32_bf16 v[86:89], v[150:153], v[208:211], v[86:89]
	v_mfma_f32_16x16x32_bf16 v[86:89], v[154:157], v[212:215], v[86:89]
	v_mfma_f32_16x16x32_bf16 v[82:85], v[150:153], v[216:219], v[82:85]
	v_mfma_f32_16x16x32_bf16 v[82:85], v[154:157], v[220:223], v[82:85]
	v_mfma_f32_16x16x32_bf16 v[54:57], v[158:161], v[216:219], v[54:57]
	v_mfma_f32_16x16x32_bf16 v[54:57], v[162:165], v[220:223], v[54:57]
	v_mfma_f32_16x16x32_bf16 v[62:65], v[158:161], v[208:211], v[62:65]
	v_mfma_f32_16x16x32_bf16 v[62:65], v[162:165], v[212:215], v[62:65]
	v_mfma_f32_16x16x32_bf16 v[74:77], v[158:161], v[200:203], v[74:77]
	v_mfma_f32_16x16x32_bf16 v[74:77], v[162:165], v[204:207], v[74:77]
	v_mfma_f32_16x16x32_bf16 v[78:81], v[158:161], v[192:195], v[78:81]
	v_mfma_f32_16x16x32_bf16 v[78:81], v[162:165], v[196:199], v[78:81]
	v_mfma_f32_16x16x32_bf16 v[30:33], v[166:169], v[192:195], v[30:33]
	v_mfma_f32_16x16x32_bf16 v[30:33], v[172:175], v[196:199], v[30:33]
	v_mfma_f32_16x16x32_bf16 v[26:29], v[166:169], v[200:203], v[26:29]
	v_mfma_f32_16x16x32_bf16 v[26:29], v[172:175], v[204:207], v[26:29]
	v_mfma_f32_16x16x32_bf16 v[22:25], v[166:169], v[208:211], v[22:25]
	v_mfma_f32_16x16x32_bf16 v[22:25], v[172:175], v[212:215], v[22:25]
	v_mfma_f32_16x16x32_bf16 v[18:21], v[166:169], v[216:219], v[18:21]
	v_mfma_f32_16x16x32_bf16 v[18:21], v[172:175], v[220:223], v[18:21]
	v_mfma_f32_16x16x32_bf16 v[2:5], v[176:179], v[216:219], v[2:5]
	v_mfma_f32_16x16x32_bf16 v[2:5], v[188:191], v[220:223], v[2:5]
	v_mfma_f32_16x16x32_bf16 v[6:9], v[176:179], v[208:211], v[6:9]
	v_mfma_f32_16x16x32_bf16 v[6:9], v[188:191], v[212:215], v[6:9]
	v_mfma_f32_16x16x32_bf16 v[10:13], v[176:179], v[200:203], v[10:13]
	v_mfma_f32_16x16x32_bf16 v[10:13], v[188:191], v[204:207], v[10:13]
	v_mfma_f32_16x16x32_bf16 v[14:17], v[176:179], v[192:195], v[14:17]
	v_mfma_f32_16x16x32_bf16 v[14:17], v[188:191], v[196:199], v[14:17]
	s_barrier
	s_setprio 0
	s_add_i32 s82, s82, 2
	s_add_u32 s74, s74, 0x100
	s_addc_u32 s75, s75, 0
	s_add_u32 s80, s80, 0x100
	s_addc_u32 s81, s81, 0
	s_cmp_gt_u32 s82, 29
	s_cbranch_scc0 .LBB0_596
	s_and_b64 vcc, exec, s[62:63]
	s_cbranch_vccz .LBB0_599
	s_barrier

; #define PG8_STAGE(bufoff, gbase, voff) do { _Pragma("unroll") for (int _i = 0; _i < 2; ++_i) \
;         __builtin_amdgcn_global_load_lds((const unsigned*)((const char*)(gbase) + (voff)[_i]), (PG8_LAS unsigned*)(lds + (bufoff) + ldsw + _i * 8192), 16, 0, 0); } while (0)
; #define PG8_LDA(dst, b, h) do { _Pragma("unroll") for (int m = 0; m < 4; ++m) _Pragma("unroll") for (int k = 0; k < 2; ++k) dst[m][k] = *(const PG8_LAS bf16x8*)(lds + PG8_SA(b, h) + aoff + m * 2048 + k * 1024); } while (0)
; #define PG8_LDB(dst, b, h) do { _Pragma("unroll") for (int n = 0; n < 2; ++n) _Pragma("unroll") for (int k = 0; k < 2; ++k) dst[n][k] = *(const PG8_LAS bf16x8*)(lds + PG8_SB(b, h) + boff + n * 2048 + k * 1024); } while (0)
; #define PG8_WAIT_L(n) asm volatile("s_waitcnt lgkmcnt(" #n ")" ::: "memory")
; #define PG8_WAIT_V_SEL(sel) asm volatile("s_cmp_eq_u32 %0, 0\n\ts_cbranch_scc1 .Lw8_%=\n\ts_waitcnt vmcnt(22)\n\ts_branch .Lwd_%=\n.Lw8_%=:\n\ts_waitcnt vmcnt(8)\n.Lwd_%=:" :: "s"(sel) : "memory", "scc")
; #define PG8_BAR __builtin_amdgcn_s_barrier()
; #define PG8_SCHED __builtin_amdgcn_sched_barrier(0)
;     ...
;             const bool last = (t == nt * KREP - 2);
;             const int t1w = KREP > 1 ? ((t + 1) & (nt - 1)) : t + 1, t2w = KREP > 1 ? ((t + 2) & (nt - 1)) : t + 2;
;             const char* a1 = cA + (size_t)t1w * kstep;
;             const char* a2 = last ? nA : cA + (size_t)t2w * kstep; const char* b2 = last ? nB : cB + (size_t)t2w * kstep;
;             const char* a3 = a2 + kstep; const char* b3 = b2 + kstep;
;             if (last && has_next) S.a_ready(nxt);
;             const int relax = __builtin_amdgcn_readfirstlane((MK_RELAXW && t == 0 && ui > 0) ? 1 : 0);
;             if constexpr (SP2) {
;             PG8_LDB(B0, 0, 0); PG8_LDB(B1, 0, 1); PG8_SCHED; PG8_LDA(At, 0, 0); PG8_STAGE(PG8_SA(1, 1), a1 + hstep, voffA);
;             PG8_WAIT_V_SEL(relax);
;             PG8_WAIT_L(0); PG8_BAR; PG8_MMA(0, 0, At, B0); PG8_MMA(0, 1, At, B1); PG8_BAR; PG8_SCHED;
;             PG8_LDA(At, 0, 1); PG8_STAGE(PG8_SB(0, 0), b2, voffB); PG8_STAGE(PG8_SB(0, 1), b2 + hstep, voffB); PG8_STAGE(PG8_SA(0, 0), a2, voffA);
;             PG8_WAIT_V_SEL(relax);
;             PG8_WAIT_L(0); PG8_BAR; PG8_MMA(1, 0, At, B0); PG8_MMA(1, 1, At, B1); PG8_BAR; PG8_SCHED;
.LBB0_1170:
	s_add_u32 s0, s78, 0xfff80080
	s_addc_u32 s1, s79, -1
	s_add_i32 s85, 0, 0x10000
	s_cmp_eq_u32 s84, 28
	s_cselect_b32 s83, s40, s1
	s_cselect_b32 s82, s41, s0
	s_cselect_b32 s81, s67, s77
	s_cselect_b32 s80, s69, s75
	s_add_i32 s86, 0, 0x14000
	ds_read_b128 v[90:93], v184
	ds_read_b128 v[94:97], v184 offset:1024
	ds_read_b128 v[98:101], v184 offset:2048
	ds_read_b128 v[102:105], v184 offset:3072
	ds_read_b128 v[146:149], v184 offset:16384
	ds_read_b128 v[150:153], v184 offset:17408
	ds_read_b128 v[154:157], v184 offset:18432
	ds_read_b128 v[158:161], v184 offset:19456
	s_add_i32 m0, s45, 0xc000
	ds_read_b128 v[162:165], v227
	ds_read_b128 v[166:169], v227 offset:1024
	ds_read_b128 v[188:191], v227 offset:2048
	ds_read_b128 v[192:195], v227 offset:3072
	ds_read_b128 v[196:199], v227 offset:4096
	ds_read_b128 v[200:203], v227 offset:5120
	ds_read_b128 v[204:207], v227 offset:6144
	ds_read_b128 v[208:211], v227 offset:7168
	global_load_lds_dwordx4 v178, s[78:79]
	s_add_i32 m0, s45, 0xe000
	s_nop 0
	global_load_lds_dwordx4 v180, s[78:79]
	s_waitcnt vmcnt(8)
	s_waitcnt lgkmcnt(0)
	.p2align 3
	s_setprio 1
	s_barrier
	v_mfma_f32_16x16x32_bf16 v[142:145], v[90:93], v[162:165], v[142:145]
	v_mfma_f32_16x16x32_bf16 v[142:145], v[94:97], v[166:169], v[142:145]
	v_mfma_f32_16x16x32_bf16 v[126:129], v[90:93], v[188:191], v[126:129]
	v_mfma_f32_16x16x32_bf16 v[126:129], v[94:97], v[192:195], v[126:129]
	v_mfma_f32_16x16x32_bf16 v[110:113], v[90:93], v[196:199], v[110:113]
	v_mfma_f32_16x16x32_bf16 v[110:113], v[94:97], v[200:203], v[110:113]
	v_mfma_f32_16x16x32_bf16 v[78:81], v[90:93], v[204:207], v[78:81]
	v_mfma_f32_16x16x32_bf16 v[78:81], v[94:97], v[208:211], v[78:81]
	v_mfma_f32_16x16x32_bf16 v[74:77], v[98:101], v[204:207], v[74:77]
	v_mfma_f32_16x16x32_bf16 v[74:77], v[102:105], v[208:211], v[74:77]
	v_mfma_f32_16x16x32_bf16 v[106:109], v[98:101], v[196:199], v[106:109]
	v_mfma_f32_16x16x32_bf16 v[106:109], v[102:105], v[200:203], v[106:109]
	v_mfma_f32_16x16x32_bf16 v[122:125], v[98:101], v[188:191], v[122:125]
	v_mfma_f32_16x16x32_bf16 v[122:125], v[102:105], v[192:195], v[122:125]
	v_mfma_f32_16x16x32_bf16 v[138:141], v[98:101], v[162:165], v[138:141]
	v_mfma_f32_16x16x32_bf16 v[138:141], v[102:105], v[166:169], v[138:141]
	v_mfma_f32_16x16x32_bf16 v[134:137], v[146:149], v[162:165], v[134:137]
	v_mfma_f32_16x16x32_bf16 v[134:137], v[150:153], v[166:169], v[134:137]
	v_mfma_f32_16x16x32_bf16 v[118:121], v[146:149], v[188:191], v[118:121]
	v_mfma_f32_16x16x32_bf16 v[118:121], v[150:153], v[192:195], v[118:121]
	v_mfma_f32_16x16x32_bf16 v[86:89], v[146:149], v[196:199], v[86:89]
	v_mfma_f32_16x16x32_bf16 v[86:89], v[150:153], v[200:203], v[86:89]
	v_mfma_f32_16x16x32_bf16 v[70:73], v[146:149], v[204:207], v[70:73]
	v_mfma_f32_16x16x32_bf16 v[70:73], v[150:153], v[208:211], v[70:73]
	v_mfma_f32_16x16x32_bf16 v[66:69], v[154:157], v[204:207], v[66:69]
	v_mfma_f32_16x16x32_bf16 v[66:69], v[158:161], v[208:211], v[66:69]
	v_mfma_f32_16x16x32_bf16 v[82:85], v[154:157], v[196:199], v[82:85]
	v_mfma_f32_16x16x32_bf16 v[82:85], v[158:161], v[200:203], v[82:85]
	v_mfma_f32_16x16x32_bf16 v[114:117], v[154:157], v[188:191], v[114:117]
	v_mfma_f32_16x16x32_bf16 v[114:117], v[158:161], v[192:195], v[114:117]
	v_mfma_f32_16x16x32_bf16 v[130:133], v[154:157], v[162:165], v[130:133]
	v_mfma_f32_16x16x32_bf16 v[130:133], v[158:161], v[166:169], v[130:133]
	s_barrier
	s_setprio 0
	s_add_i32 s0, s85, s33
	s_mov_b32 m0, s0
	ds_read_b128 v[162:165], v227 offset:16384
	ds_read_b128 v[166:169], v227 offset:17408
	ds_read_b128 v[188:191], v227 offset:18432
	ds_read_b128 v[192:195], v227 offset:19456
	ds_read_b128 v[196:199], v227 offset:20480
	ds_read_b128 v[200:203], v227 offset:21504
	ds_read_b128 v[204:207], v227 offset:22528
	ds_read_b128 v[208:211], v227 offset:23552
	global_load_lds_dwordx4 v182, s[80:81]
	s_add_i32 m0, s0, 0x2000
	s_add_u32 s0, s80, 0x80000
	s_addc_u32 s1, s81, 0
	s_add_i32 s85, s86, s33
	global_load_lds_dwordx4 v176, s[80:81]
	s_mov_b32 m0, s85
	s_nop 0
	global_load_lds_dwordx4 v182, s[0:1]
	s_add_i32 m0, s85, 0x2000
	s_nop 0
	global_load_lds_dwordx4 v176, s[0:1]
	s_mov_b32 m0, s45
	s_nop 0
	global_load_lds_dwordx4 v172, s[82:83]
	s_mov_b32 m0, s46
	s_nop 0
	global_load_lds_dwordx4 v174, s[82:83]
	s_waitcnt vmcnt(8)
	s_waitcnt lgkmcnt(0)
	.p2align 3
	s_setprio 1
	s_barrier
	v_mfma_f32_16x16x32_bf16 v[62:65], v[90:93], v[162:165], v[62:65]
	v_mfma_f32_16x16x32_bf16 v[62:65], v[94:97], v[166:169], v[62:65]
	v_mfma_f32_16x16x32_bf16 v[46:49], v[90:93], v[188:191], v[46:49]
	v_mfma_f32_16x16x32_bf16 v[46:49], v[94:97], v[192:195], v[46:49]
	v_mfma_f32_16x16x32_bf16 v[30:33], v[90:93], v[196:199], v[30:33]
	v_mfma_f32_16x16x32_bf16 v[30:33], v[94:97], v[200:203], v[30:33]
	v_mfma_f32_16x16x32_bf16 v[14:17], v[90:93], v[204:207], v[14:17]
	v_mfma_f32_16x16x32_bf16 v[14:17], v[94:97], v[208:211], v[14:17]
	v_mfma_f32_16x16x32_bf16 v[10:13], v[98:101], v[204:207], v[10:13]
	v_mfma_f32_16x16x32_bf16 v[10:13], v[102:105], v[208:211], v[10:13]
	v_mfma_f32_16x16x32_bf16 v[26:29], v[98:101], v[196:199], v[26:29]
	v_mfma_f32_16x16x32_bf16 v[26:29], v[102:105], v[200:203], v[26:29]
	v_mfma_f32_16x16x32_bf16 v[42:45], v[98:101], v[188:191], v[42:45]
	v_mfma_f32_16x16x32_bf16 v[42:45], v[102:105], v[192:195], v[42:45]
	v_mfma_f32_16x16x32_bf16 v[58:61], v[98:101], v[162:165], v[58:61]
	v_mfma_f32_16x16x32_bf16 v[58:61], v[102:105], v[166:169], v[58:61]
	v_mfma_f32_16x16x32_bf16 v[54:57], v[146:149], v[162:165], v[54:57]
	v_mfma_f32_16x16x32_bf16 v[54:57], v[150:153], v[166:169], v[54:57]
	v_mfma_f32_16x16x32_bf16 v[38:41], v[146:149], v[188:191], v[38:41]
	v_mfma_f32_16x16x32_bf16 v[38:41], v[150:153], v[192:195], v[38:41]
	v_mfma_f32_16x16x32_bf16 v[22:25], v[146:149], v[196:199], v[22:25]
	v_mfma_f32_16x16x32_bf16 v[22:25], v[150:153], v[200:203], v[22:25]
	v_mfma_f32_16x16x32_bf16 v[6:9], v[146:149], v[204:207], v[6:9]
	v_mfma_f32_16x16x32_bf16 v[6:9], v[150:153], v[208:211], v[6:9]
	v_mfma_f32_16x16x32_bf16 v[2:5], v[154:157], v[204:207], v[2:5]
	v_mfma_f32_16x16x32_bf16 v[2:5], v[158:161], v[208:211], v[2:5]
	v_mfma_f32_16x16x32_bf16 v[18:21], v[154:157], v[196:199], v[18:21]
	v_mfma_f32_16x16x32_bf16 v[18:21], v[158:161], v[200:203], v[18:21]
	v_mfma_f32_16x16x32_bf16 v[34:37], v[154:157], v[188:191], v[34:37]
	v_mfma_f32_16x16x32_bf16 v[34:37], v[158:161], v[192:195], v[34:37]
	v_mfma_f32_16x16x32_bf16 v[50:53], v[154:157], v[162:165], v[50:53]
	v_mfma_f32_16x16x32_bf16 v[50:53], v[158:161], v[166:169], v[50:53]
	s_barrier
; #define PG8_STAGE(bufoff, gbase, voff) do { _Pragma("unroll") for (int _i = 0; _i < 2; ++_i) \
;         __builtin_amdgcn_global_load_lds((const unsigned*)((const char*)(gbase) + (voff)[_i]), (PG8_LAS unsigned*)(lds + (bufoff) + ldsw + _i * 8192), 16, 0, 0); } while (0)
; #define PG8_LDA(dst, b, h) do { _Pragma("unroll") for (int m = 0; m < 4; ++m) _Pragma("unroll") for (int k = 0; k < 2; ++k) dst[m][k] = *(const PG8_LAS bf16x8*)(lds + PG8_SA(b, h) + aoff + m * 2048 + k * 1024); } while (0)
; #define PG8_LDB(dst, b, h) do { _Pragma("unroll") for (int n = 0; n < 2; ++n) _Pragma("unroll") for (int k = 0; k < 2; ++k) dst[n][k] = *(const PG8_LAS bf16x8*)(lds + PG8_SB(b, h) + boff + n * 2048 + k * 1024); } while (0)
; #define PG8_WAIT_V(n) asm volatile("s_waitcnt vmcnt(" #n ")" ::: "memory")
; #define PG8_WAIT_L(n) asm volatile("s_waitcnt lgkmcnt(" #n ")" ::: "memory")
; #define PG8_BAR __builtin_amdgcn_s_barrier()
; #define PG8_SCHED __builtin_amdgcn_sched_barrier(0)
;     ...
;             PG8_WAIT_L(0); PG8_BAR; PG8_MMA(1, 0, At, B0); PG8_MMA(1, 1, At, B1); PG8_BAR; PG8_SCHED;
;             PG8_LDB(B0, 1, 0); PG8_LDB(B1, 1, 1); PG8_SCHED; PG8_LDA(At, 1, 0); PG8_STAGE(PG8_SA(0, 1), a2 + hstep, voffA);
;             PG8_WAIT_V(8); PG8_WAIT_L(0); PG8_BAR; PG8_MMA(0, 0, At, B0); PG8_MMA(0, 1, At, B1); PG8_BAR; PG8_SCHED;
;             PG8_LDA(At, 1, 1); PG8_STAGE(PG8_SB(1, 0), b3, voffB); PG8_STAGE(PG8_SB(1, 1), b3 + hstep, voffB); PG8_STAGE(PG8_SA(1, 0), a3, voffA);
;             PG8_WAIT_V(8); PG8_WAIT_L(0); PG8_BAR; PG8_MMA(1, 0, At, B0); PG8_MMA(1, 1, At, B1); PG8_BAR; PG8_SCHED;
	s_setprio 0
	s_add_i32 s85, 0, 0x18000
	s_add_i32 s86, 0, 0x1c000
	ds_read_b128 v[90:93], v184 offset:32768
	ds_read_b128 v[94:97], v184 offset:33792
	ds_read_b128 v[98:101], v184 offset:34816
	ds_read_b128 v[102:105], v184 offset:35840
	ds_read_b128 v[146:149], v184 offset:49152
	ds_read_b128 v[150:153], v184 offset:50176
	ds_read_b128 v[154:157], v184 offset:51200
	ds_read_b128 v[158:161], v184 offset:52224
	s_add_u32 s0, s82, 0x80000
	s_addc_u32 s1, s83, 0
	s_mov_b32 m0, s47
	ds_read_b128 v[162:165], v227 offset:32768
	ds_read_b128 v[166:169], v227 offset:33792
	ds_read_b128 v[188:191], v227 offset:34816
	ds_read_b128 v[192:195], v227 offset:35840
	ds_read_b128 v[196:199], v227 offset:36864
	ds_read_b128 v[200:203], v227 offset:37888
	ds_read_b128 v[204:207], v227 offset:38912
	ds_read_b128 v[208:211], v227 offset:39936
	global_load_lds_dwordx4 v172, s[0:1]
	s_mov_b32 m0, s48
	s_nop 0
	global_load_lds_dwordx4 v174, s[0:1]
	s_waitcnt vmcnt(8)
	s_waitcnt lgkmcnt(0)
	.p2align 3
	s_setprio 1
	s_barrier
	v_mfma_f32_16x16x32_bf16 v[142:145], v[90:93], v[162:165], v[142:145]
	v_mfma_f32_16x16x32_bf16 v[142:145], v[94:97], v[166:169], v[142:145]
	v_mfma_f32_16x16x32_bf16 v[126:129], v[90:93], v[188:191], v[126:129]
	v_mfma_f32_16x16x32_bf16 v[126:129], v[94:97], v[192:195], v[126:129]
	v_mfma_f32_16x16x32_bf16 v[110:113], v[90:93], v[196:199], v[110:113]
	v_mfma_f32_16x16x32_bf16 v[110:113], v[94:97], v[200:203], v[110:113]
	v_mfma_f32_16x16x32_bf16 v[78:81], v[90:93], v[204:207], v[78:81]
	v_mfma_f32_16x16x32_bf16 v[78:81], v[94:97], v[208:211], v[78:81]
	v_mfma_f32_16x16x32_bf16 v[74:77], v[98:101], v[204:207], v[74:77]
	v_mfma_f32_16x16x32_bf16 v[74:77], v[102:105], v[208:211], v[74:77]
	v_mfma_f32_16x16x32_bf16 v[106:109], v[98:101], v[196:199], v[106:109]
	v_mfma_f32_16x16x32_bf16 v[106:109], v[102:105], v[200:203], v[106:109]
	v_mfma_f32_16x16x32_bf16 v[122:125], v[98:101], v[188:191], v[122:125]
	v_mfma_f32_16x16x32_bf16 v[122:125], v[102:105], v[192:195], v[122:125]
	v_mfma_f32_16x16x32_bf16 v[138:141], v[98:101], v[162:165], v[138:141]
	v_mfma_f32_16x16x32_bf16 v[138:141], v[102:105], v[166:169], v[138:141]
	v_mfma_f32_16x16x32_bf16 v[134:137], v[146:149], v[162:165], v[134:137]
	v_mfma_f32_16x16x32_bf16 v[134:137], v[150:153], v[166:169], v[134:137]
	v_mfma_f32_16x16x32_bf16 v[118:121], v[146:149], v[188:191], v[118:121]
	v_mfma_f32_16x16x32_bf16 v[118:121], v[150:153], v[192:195], v[118:121]
	v_mfma_f32_16x16x32_bf16 v[86:89], v[146:149], v[196:199], v[86:89]
	v_mfma_f32_16x16x32_bf16 v[86:89], v[150:153], v[200:203], v[86:89]
	v_mfma_f32_16x16x32_bf16 v[70:73], v[146:149], v[204:207], v[70:73]
	v_mfma_f32_16x16x32_bf16 v[70:73], v[150:153], v[208:211], v[70:73]
	v_mfma_f32_16x16x32_bf16 v[66:69], v[154:157], v[204:207], v[66:69]
	v_mfma_f32_16x16x32_bf16 v[66:69], v[158:161], v[208:211], v[66:69]
	v_mfma_f32_16x16x32_bf16 v[82:85], v[154:157], v[196:199], v[82:85]
	v_mfma_f32_16x16x32_bf16 v[82:85], v[158:161], v[200:203], v[82:85]
	v_mfma_f32_16x16x32_bf16 v[114:117], v[154:157], v[188:191], v[114:117]
	v_mfma_f32_16x16x32_bf16 v[114:117], v[158:161], v[192:195], v[114:117]
	v_mfma_f32_16x16x32_bf16 v[130:133], v[154:157], v[162:165], v[130:133]
	v_mfma_f32_16x16x32_bf16 v[130:133], v[158:161], v[166:169], v[130:133]
	s_barrier
	s_setprio 0
	s_add_i32 s0, s85, s33
	s_mov_b32 m0, s0
	ds_read_b128 v[162:165], v227 offset:49152
	ds_read_b128 v[166:169], v227 offset:50176
	ds_read_b128 v[188:191], v227 offset:51200
	ds_read_b128 v[192:195], v227 offset:52224
	ds_read_b128 v[196:199], v227 offset:53248
	ds_read_b128 v[200:203], v227 offset:54272
	ds_read_b128 v[204:207], v227 offset:55296
	ds_read_b128 v[208:211], v227 offset:56320
	s_add_u32 s100, s80, 0x80
	s_addc_u32 s101, s81, 0
	global_load_lds_dwordx4 v182, s[100:101]
	s_add_i32 m0, s0, 0x2000
	s_add_u32 s0, s80, 0x80080
	s_addc_u32 s1, s81, 0
	s_add_i32 s80, s86, s33
	global_load_lds_dwordx4 v176, s[100:101]
	s_mov_b32 m0, s80
	s_nop 0
	global_load_lds_dwordx4 v182, s[0:1]
	s_add_i32 m0, s80, 0x2000
	s_nop 0
	global_load_lds_dwordx4 v176, s[0:1]
	s_mov_b32 m0, s50
	s_nop 0
	s_add_u32 s100, s82, 0x80
	s_addc_u32 s101, s83, 0
	global_load_lds_dwordx4 v172, s[100:101]
	s_mov_b32 m0, s51
	s_nop 0
	global_load_lds_dwordx4 v174, s[100:101]
	s_waitcnt vmcnt(8)
	s_waitcnt lgkmcnt(0)
	.p2align 3
	s_setprio 1
	s_barrier
	v_mfma_f32_16x16x32_bf16 v[62:65], v[90:93], v[162:165], v[62:65]
	v_mfma_f32_16x16x32_bf16 v[62:65], v[94:97], v[166:169], v[62:65]
	v_mfma_f32_16x16x32_bf16 v[46:49], v[90:93], v[188:191], v[46:49]
	v_mfma_f32_16x16x32_bf16 v[46:49], v[94:97], v[192:195], v[46:49]
	v_mfma_f32_16x16x32_bf16 v[30:33], v[90:93], v[196:199], v[30:33]
	v_mfma_f32_16x16x32_bf16 v[30:33], v[94:97], v[200:203], v[30:33]
	v_mfma_f32_16x16x32_bf16 v[14:17], v[90:93], v[204:207], v[14:17]
	v_mfma_f32_16x16x32_bf16 v[14:17], v[94:97], v[208:211], v[14:17]
	v_mfma_f32_16x16x32_bf16 v[10:13], v[98:101], v[204:207], v[10:13]
	v_mfma_f32_16x16x32_bf16 v[10:13], v[102:105], v[208:211], v[10:13]
	v_mfma_f32_16x16x32_bf16 v[26:29], v[98:101], v[196:199], v[26:29]
	v_mfma_f32_16x16x32_bf16 v[26:29], v[102:105], v[200:203], v[26:29]
	v_mfma_f32_16x16x32_bf16 v[42:45], v[98:101], v[188:191], v[42:45]
	v_mfma_f32_16x16x32_bf16 v[42:45], v[102:105], v[192:195], v[42:45]
	v_mfma_f32_16x16x32_bf16 v[58:61], v[98:101], v[162:165], v[58:61]
	v_mfma_f32_16x16x32_bf16 v[58:61], v[102:105], v[166:169], v[58:61]
	v_mfma_f32_16x16x32_bf16 v[54:57], v[146:149], v[162:165], v[54:57]
	v_mfma_f32_16x16x32_bf16 v[54:57], v[150:153], v[166:169], v[54:57]
	v_mfma_f32_16x16x32_bf16 v[38:41], v[146:149], v[188:191], v[38:41]
	v_mfma_f32_16x16x32_bf16 v[38:41], v[150:153], v[192:195], v[38:41]
	v_mfma_f32_16x16x32_bf16 v[22:25], v[146:149], v[196:199], v[22:25]
	v_mfma_f32_16x16x32_bf16 v[22:25], v[150:153], v[200:203], v[22:25]
	v_mfma_f32_16x16x32_bf16 v[6:9], v[146:149], v[204:207], v[6:9]
	v_mfma_f32_16x16x32_bf16 v[6:9], v[150:153], v[208:211], v[6:9]
	v_mfma_f32_16x16x32_bf16 v[2:5], v[154:157], v[204:207], v[2:5]
	v_mfma_f32_16x16x32_bf16 v[2:5], v[158:161], v[208:211], v[2:5]
	v_mfma_f32_16x16x32_bf16 v[18:21], v[154:157], v[196:199], v[18:21]
	v_mfma_f32_16x16x32_bf16 v[18:21], v[158:161], v[200:203], v[18:21]
	v_mfma_f32_16x16x32_bf16 v[34:37], v[154:157], v[188:191], v[34:37]
	v_mfma_f32_16x16x32_bf16 v[34:37], v[158:161], v[192:195], v[34:37]
	v_mfma_f32_16x16x32_bf16 v[50:53], v[154:157], v[162:165], v[50:53]
	v_mfma_f32_16x16x32_bf16 v[50:53], v[158:161], v[166:169], v[50:53]
	s_barrier
	s_setprio 0
	s_add_i32 s84, s84, 2
	s_add_u32 s78, s78, 0x100
	s_addc_u32 s79, s79, 0
	s_add_u32 s75, s75, 0x100
	s_addc_u32 s77, s77, 0
	s_cmp_gt_u32 s84, 29
	s_cbranch_scc0 .LBB0_1170
	s_and_b64 vcc, exec, s[64:65]
	s_cbranch_vccz .LBB0_1173
	s_barrier

; #define PG8_STAGE(bufoff, gbase, voff) do { _Pragma("unroll") for (int _i = 0; _i < 2; ++_i) \
;         __builtin_amdgcn_global_load_lds((const unsigned*)((const char*)(gbase) + (voff)[_i]), (PG8_LAS unsigned*)(lds + (bufoff) + ldsw + _i * 8192), 16, 0, 0); } while (0)
; #define PG8_LDA(dst, b, h) do { _Pragma("unroll") for (int m = 0; m < 4; ++m) _Pragma("unroll") for (int k = 0; k < 2; ++k) dst[m][k] = *(const PG8_LAS bf16x8*)(lds + PG8_SA(b, h) + aoff + m * 2048 + k * 1024); } while (0)
; #define PG8_WAIT_L(n) asm volatile("s_waitcnt lgkmcnt(" #n ")" ::: "memory")
; #define PG8_WAIT_V_SEL(sel) asm volatile("s_cmp_eq_u32 %0, 0\n\ts_cbranch_scc1 .Lw8_%=\n\ts_waitcnt vmcnt(22)\n\ts_branch .Lwd_%=\n.Lw8_%=:\n\ts_waitcnt vmcnt(8)\n.Lwd_%=:" :: "s"(sel) : "memory", "scc")
; #define PG8_BAR __builtin_amdgcn_s_barrier()
; #define PG8_SCHED __builtin_amdgcn_sched_barrier(0)
;     ...
;             PG8_WAIT_L(0); PG8_BAR; PG8_MMA(0, 0, At, B0); PG8_MMA(0, 1, At, B1); PG8_BAR; PG8_SCHED;
;             PG8_LDA(At, 0, 1); PG8_STAGE(PG8_SB(0, 0), b2, voffB); PG8_STAGE(PG8_SB(0, 1), b2 + hstep, voffB); PG8_STAGE(PG8_SA(0, 0), a2, voffA);
;             PG8_WAIT_V_SEL(relax);
;             PG8_WAIT_L(0); PG8_BAR; PG8_MMA(1, 0, At, B0); PG8_MMA(1, 1, At, B1); PG8_BAR; PG8_SCHED;
.Lrlx_f1_0_b:
	s_waitcnt lgkmcnt(0)
	.p2align 3
	s_setprio 1
	s_barrier
	v_mfma_f32_16x16x32_bf16 v[114:117], v[66:69], v[162:165], v[114:117]
	v_mfma_f32_16x16x32_bf16 v[114:117], v[70:73], v[166:169], v[114:117]
	v_mfma_f32_16x16x32_bf16 v[110:113], v[66:69], v[170:173], v[110:113]
	v_mfma_f32_16x16x32_bf16 v[110:113], v[70:73], v[174:177], v[110:113]
	v_mfma_f32_16x16x32_bf16 v[78:81], v[66:69], v[178:181], v[78:81]
	v_mfma_f32_16x16x32_bf16 v[78:81], v[70:73], v[184:187], v[78:81]
	v_mfma_f32_16x16x32_bf16 v[74:77], v[66:69], v[220:223], v[74:77]
	v_mfma_f32_16x16x32_bf16 v[74:77], v[70:73], v[224:227], v[74:77]
	v_mfma_f32_16x16x32_bf16 v[134:137], v[82:85], v[220:223], v[134:137]
	v_mfma_f32_16x16x32_bf16 v[134:137], v[142:145], v[224:227], v[134:137]
	v_mfma_f32_16x16x32_bf16 v[138:141], v[82:85], v[178:181], v[138:141]
	v_mfma_f32_16x16x32_bf16 v[138:141], v[142:145], v[184:187], v[138:141]
	v_mfma_f32_16x16x32_bf16 v[102:105], v[82:85], v[170:173], v[102:105]
	v_mfma_f32_16x16x32_bf16 v[102:105], v[142:145], v[174:177], v[102:105]
	v_mfma_f32_16x16x32_bf16 v[106:109], v[82:85], v[162:165], v[106:109]
	v_mfma_f32_16x16x32_bf16 v[106:109], v[142:145], v[166:169], v[106:109]
	v_mfma_f32_16x16x32_bf16 v[98:101], v[146:149], v[162:165], v[98:101]
	v_mfma_f32_16x16x32_bf16 v[98:101], v[150:153], v[166:169], v[98:101]
	v_mfma_f32_16x16x32_bf16 v[94:97], v[146:149], v[170:173], v[94:97]
	v_mfma_f32_16x16x32_bf16 v[94:97], v[150:153], v[174:177], v[94:97]
	v_mfma_f32_16x16x32_bf16 v[130:133], v[146:149], v[178:181], v[130:133]
	v_mfma_f32_16x16x32_bf16 v[130:133], v[150:153], v[184:187], v[130:133]
	v_mfma_f32_16x16x32_bf16 v[126:129], v[146:149], v[220:223], v[126:129]
	v_mfma_f32_16x16x32_bf16 v[126:129], v[150:153], v[224:227], v[126:129]
	v_mfma_f32_16x16x32_bf16 v[118:121], v[154:157], v[220:223], v[118:121]
	v_mfma_f32_16x16x32_bf16 v[118:121], v[158:161], v[224:227], v[118:121]
	v_mfma_f32_16x16x32_bf16 v[122:125], v[154:157], v[178:181], v[122:125]
	v_mfma_f32_16x16x32_bf16 v[122:125], v[158:161], v[184:187], v[122:125]
	v_mfma_f32_16x16x32_bf16 v[86:89], v[154:157], v[170:173], v[86:89]
	v_mfma_f32_16x16x32_bf16 v[86:89], v[158:161], v[174:177], v[86:89]
	v_mfma_f32_16x16x32_bf16 v[90:93], v[154:157], v[162:165], v[90:93]
	v_mfma_f32_16x16x32_bf16 v[90:93], v[158:161], v[166:169], v[90:93]
	s_barrier
	s_setprio 0
	s_add_i32 s12, s51, s37
	s_mov_b32 m0, s12
	ds_read_b128 v[162:165], v219 offset:16384
	ds_read_b128 v[166:169], v219 offset:17408
	ds_read_b128 v[170:173], v219 offset:18432
	ds_read_b128 v[174:177], v219 offset:19456
	ds_read_b128 v[178:181], v219 offset:20480
	ds_read_b128 v[184:187], v219 offset:21504
	ds_read_b128 v[220:223], v219 offset:22528
	ds_read_b128 v[224:227], v219 offset:23552
	global_load_lds_dwordx4 v182, vcc
	s_add_i32 m0, s12, 0x2000
	s_add_u32 s12, vcc_lo, 0x80000
	s_addc_u32 s13, vcc_hi, 0
	s_add_i32 s19, s19, s37
	global_load_lds_dwordx4 v192, vcc
	s_mov_b32 m0, s19
	s_nop 0
	global_load_lds_dwordx4 v182, s[12:13]
	s_add_i32 m0, s19, 0x2000
	s_nop 0
	global_load_lds_dwordx4 v192, s[12:13]
	s_mov_b32 m0, s95
	s_nop 0
	global_load_lds_dwordx4 v188, s[40:41]
	s_mov_b32 m0, s20
	s_nop 0
	global_load_lds_dwordx4 v190, s[40:41]
	s_cmp_eq_u32 s101, 1
	s_cbranch_scc1 .Lrlx_f1_1
	s_waitcnt vmcnt(8)
.Lrlx_f1_1_b:
	s_waitcnt lgkmcnt(0)
	.p2align 3
	s_setprio 1
	s_barrier
	v_mfma_f32_16x16x32_bf16 v[30:33], v[66:69], v[162:165], v[30:33]
	v_mfma_f32_16x16x32_bf16 v[30:33], v[70:73], v[166:169], v[30:33]
	v_mfma_f32_16x16x32_bf16 v[26:29], v[66:69], v[170:173], v[26:29]
	v_mfma_f32_16x16x32_bf16 v[26:29], v[70:73], v[174:177], v[26:29]
	v_mfma_f32_16x16x32_bf16 v[62:65], v[66:69], v[178:181], v[62:65]
	v_mfma_f32_16x16x32_bf16 v[62:65], v[70:73], v[184:187], v[62:65]
	v_mfma_f32_16x16x32_bf16 v[58:61], v[66:69], v[220:223], v[58:61]
	v_mfma_f32_16x16x32_bf16 v[58:61], v[70:73], v[224:227], v[58:61]
	v_mfma_f32_16x16x32_bf16 v[50:53], v[82:85], v[220:223], v[50:53]
	v_mfma_f32_16x16x32_bf16 v[50:53], v[142:145], v[224:227], v[50:53]
	v_mfma_f32_16x16x32_bf16 v[54:57], v[82:85], v[178:181], v[54:57]
	v_mfma_f32_16x16x32_bf16 v[54:57], v[142:145], v[184:187], v[54:57]
	v_mfma_f32_16x16x32_bf16 v[18:21], v[82:85], v[170:173], v[18:21]
	v_mfma_f32_16x16x32_bf16 v[18:21], v[142:145], v[174:177], v[18:21]
	v_mfma_f32_16x16x32_bf16 v[22:25], v[82:85], v[162:165], v[22:25]
	v_mfma_f32_16x16x32_bf16 v[22:25], v[142:145], v[166:169], v[22:25]
	v_mfma_f32_16x16x32_bf16 v[14:17], v[146:149], v[162:165], v[14:17]
	v_mfma_f32_16x16x32_bf16 v[14:17], v[150:153], v[166:169], v[14:17]
	v_mfma_f32_16x16x32_bf16 v[10:13], v[146:149], v[170:173], v[10:13]
	v_mfma_f32_16x16x32_bf16 v[10:13], v[150:153], v[174:177], v[10:13]
	v_mfma_f32_16x16x32_bf16 v[46:49], v[146:149], v[178:181], v[46:49]
	v_mfma_f32_16x16x32_bf16 v[46:49], v[150:153], v[184:187], v[46:49]
	v_mfma_f32_16x16x32_bf16 v[38:41], v[146:149], v[220:223], v[38:41]
	v_mfma_f32_16x16x32_bf16 v[38:41], v[150:153], v[224:227], v[38:41]
	v_mfma_f32_16x16x32_bf16 v[42:45], v[154:157], v[220:223], v[42:45]
	v_mfma_f32_16x16x32_bf16 v[42:45], v[158:161], v[224:227], v[42:45]
	v_mfma_f32_16x16x32_bf16 v[34:37], v[154:157], v[178:181], v[34:37]
	v_mfma_f32_16x16x32_bf16 v[34:37], v[158:161], v[184:187], v[34:37]
	v_mfma_f32_16x16x32_bf16 v[2:5], v[154:157], v[170:173], v[2:5]
	v_mfma_f32_16x16x32_bf16 v[2:5], v[158:161], v[174:177], v[2:5]
	v_mfma_f32_16x16x32_bf16 v[6:9], v[154:157], v[162:165], v[6:9]
	v_mfma_f32_16x16x32_bf16 v[6:9], v[158:161], v[166:169], v[6:9]
	s_barrier
; #define PG8_STAGE(bufoff, gbase, voff) do { _Pragma("unroll") for (int _i = 0; _i < 2; ++_i) \
;         __builtin_amdgcn_global_load_lds((const unsigned*)((const char*)(gbase) + (voff)[_i]), (PG8_LAS unsigned*)(lds + (bufoff) + ldsw + _i * 8192), 16, 0, 0); } while (0)
; #define PG8_LDA(dst, b, h) do { _Pragma("unroll") for (int m = 0; m < 4; ++m) _Pragma("unroll") for (int k = 0; k < 2; ++k) dst[m][k] = *(const PG8_LAS bf16x8*)(lds + PG8_SA(b, h) + aoff + m * 2048 + k * 1024); } while (0)
; #define PG8_LDB(dst, b, h) do { _Pragma("unroll") for (int n = 0; n < 2; ++n) _Pragma("unroll") for (int k = 0; k < 2; ++k) dst[n][k] = *(const PG8_LAS bf16x8*)(lds + PG8_SB(b, h) + boff + n * 2048 + k * 1024); } while (0)
; #define PG8_WAIT_V(n) asm volatile("s_waitcnt vmcnt(" #n ")" ::: "memory")
; #define PG8_WAIT_L(n) asm volatile("s_waitcnt lgkmcnt(" #n ")" ::: "memory")
; #define PG8_BAR __builtin_amdgcn_s_barrier()
; #define PG8_SCHED __builtin_amdgcn_sched_barrier(0)
;     ...
;             PG8_WAIT_L(0); PG8_BAR; PG8_MMA(1, 0, At, B0); PG8_MMA(1, 1, At, B1); PG8_BAR; PG8_SCHED;
;             PG8_LDB(B0, 1, 0); PG8_LDB(B1, 1, 1); PG8_SCHED; PG8_LDA(At, 1, 0); PG8_STAGE(PG8_SA(0, 1), a2 + hstep, voffA);
;             PG8_WAIT_V(8); PG8_WAIT_L(0); PG8_BAR; PG8_MMA(0, 0, At, B0); PG8_MMA(0, 1, At, B1); PG8_BAR; PG8_SCHED;
;             PG8_LDA(At, 1, 1); PG8_STAGE(PG8_SB(1, 0), b3, voffB); PG8_STAGE(PG8_SB(1, 1), b3 + hstep, voffB); PG8_STAGE(PG8_SA(1, 0), a3, voffA);
;             PG8_WAIT_V(8); PG8_WAIT_L(0); PG8_BAR; PG8_MMA(1, 0, At, B0); PG8_MMA(1, 1, At, B1); PG8_BAR; PG8_SCHED;
	s_setprio 0
	s_add_i32 s19, 0, 0x18000
	s_add_i32 s51, 0, 0x1c000
	ds_read_b128 v[66:69], v200 offset:32768
	ds_read_b128 v[70:73], v200 offset:33792
	ds_read_b128 v[82:85], v200 offset:34816
	ds_read_b128 v[142:145], v200 offset:35840
	ds_read_b128 v[146:149], v200 offset:49152
	ds_read_b128 v[150:153], v200 offset:50176
	ds_read_b128 v[154:157], v200 offset:51200
	ds_read_b128 v[158:161], v200 offset:52224
	s_add_u32 s12, s40, 0x80000
	s_addc_u32 s13, s41, 0
	s_mov_b32 m0, s44
	ds_read_b128 v[162:165], v219 offset:32768
	ds_read_b128 v[166:169], v219 offset:33792
	ds_read_b128 v[170:173], v219 offset:34816
	ds_read_b128 v[174:177], v219 offset:35840
	ds_read_b128 v[178:181], v219 offset:36864
	ds_read_b128 v[184:187], v219 offset:37888
	ds_read_b128 v[220:223], v219 offset:38912
	ds_read_b128 v[224:227], v219 offset:39936
	global_load_lds_dwordx4 v188, s[12:13]
	s_mov_b32 m0, s46
	s_nop 0
	global_load_lds_dwordx4 v190, s[12:13]
	s_waitcnt vmcnt(8)
	s_waitcnt lgkmcnt(0)
	.p2align 3
	s_setprio 1
	s_barrier
	v_mfma_f32_16x16x32_bf16 v[114:117], v[66:69], v[162:165], v[114:117]
	v_mfma_f32_16x16x32_bf16 v[114:117], v[70:73], v[166:169], v[114:117]
	v_mfma_f32_16x16x32_bf16 v[110:113], v[66:69], v[170:173], v[110:113]
	v_mfma_f32_16x16x32_bf16 v[110:113], v[70:73], v[174:177], v[110:113]
	v_mfma_f32_16x16x32_bf16 v[78:81], v[66:69], v[178:181], v[78:81]
	v_mfma_f32_16x16x32_bf16 v[78:81], v[70:73], v[184:187], v[78:81]
	v_mfma_f32_16x16x32_bf16 v[74:77], v[66:69], v[220:223], v[74:77]
	v_mfma_f32_16x16x32_bf16 v[74:77], v[70:73], v[224:227], v[74:77]
	v_mfma_f32_16x16x32_bf16 v[134:137], v[82:85], v[220:223], v[134:137]
	v_mfma_f32_16x16x32_bf16 v[134:137], v[142:145], v[224:227], v[134:137]
	v_mfma_f32_16x16x32_bf16 v[138:141], v[82:85], v[178:181], v[138:141]
	v_mfma_f32_16x16x32_bf16 v[138:141], v[142:145], v[184:187], v[138:141]
	v_mfma_f32_16x16x32_bf16 v[102:105], v[82:85], v[170:173], v[102:105]
	v_mfma_f32_16x16x32_bf16 v[102:105], v[142:145], v[174:177], v[102:105]
	v_mfma_f32_16x16x32_bf16 v[106:109], v[82:85], v[162:165], v[106:109]
	v_mfma_f32_16x16x32_bf16 v[106:109], v[142:145], v[166:169], v[106:109]
	v_mfma_f32_16x16x32_bf16 v[98:101], v[146:149], v[162:165], v[98:101]
	v_mfma_f32_16x16x32_bf16 v[98:101], v[150:153], v[166:169], v[98:101]
	v_mfma_f32_16x16x32_bf16 v[94:97], v[146:149], v[170:173], v[94:97]
	v_mfma_f32_16x16x32_bf16 v[94:97], v[150:153], v[174:177], v[94:97]
	v_mfma_f32_16x16x32_bf16 v[130:133], v[146:149], v[178:181], v[130:133]
	v_mfma_f32_16x16x32_bf16 v[130:133], v[150:153], v[184:187], v[130:133]
	v_mfma_f32_16x16x32_bf16 v[126:129], v[146:149], v[220:223], v[126:129]
	v_mfma_f32_16x16x32_bf16 v[126:129], v[150:153], v[224:227], v[126:129]
	v_mfma_f32_16x16x32_bf16 v[118:121], v[154:157], v[220:223], v[118:121]
	v_mfma_f32_16x16x32_bf16 v[118:121], v[158:161], v[224:227], v[118:121]
	v_mfma_f32_16x16x32_bf16 v[122:125], v[154:157], v[178:181], v[122:125]
	v_mfma_f32_16x16x32_bf16 v[122:125], v[158:161], v[184:187], v[122:125]
	v_mfma_f32_16x16x32_bf16 v[86:89], v[154:157], v[170:173], v[86:89]
	v_mfma_f32_16x16x32_bf16 v[86:89], v[158:161], v[174:177], v[86:89]
	v_mfma_f32_16x16x32_bf16 v[90:93], v[154:157], v[162:165], v[90:93]
	v_mfma_f32_16x16x32_bf16 v[90:93], v[158:161], v[166:169], v[90:93]
	s_barrier
	s_setprio 0
	s_add_i32 s12, s19, s37
	s_mov_b32 m0, s12
	ds_read_b128 v[162:165], v219 offset:49152
	ds_read_b128 v[166:169], v219 offset:50176
	ds_read_b128 v[170:173], v219 offset:51200
	ds_read_b128 v[174:177], v219 offset:52224
	ds_read_b128 v[178:181], v219 offset:53248
	ds_read_b128 v[184:187], v219 offset:54272
	ds_read_b128 v[220:223], v219 offset:55296
	ds_read_b128 v[224:227], v219 offset:56320
	s_add_u32 s100, vcc_lo, 0x80
	s_addc_u32 s101, vcc_hi, 0
	global_load_lds_dwordx4 v182, s[100:101]
	s_add_i32 m0, s12, 0x2000
	s_add_u32 s12, vcc_lo, 0x80080
	s_addc_u32 s13, vcc_hi, 0
	s_add_i32 s19, s51, s37
	global_load_lds_dwordx4 v192, s[100:101]
	s_mov_b32 m0, s19
	s_nop 0
	global_load_lds_dwordx4 v182, s[12:13]
	s_add_i32 m0, s19, 0x2000
	s_nop 0
	global_load_lds_dwordx4 v192, s[12:13]
	s_mov_b32 m0, s45
	s_nop 0
	s_add_u32 s100, s40, 0x80
	s_addc_u32 s101, s41, 0
	global_load_lds_dwordx4 v188, s[100:101]
	s_mov_b32 m0, s24
	s_nop 0
	global_load_lds_dwordx4 v190, s[100:101]
	s_waitcnt vmcnt(8)
	s_waitcnt lgkmcnt(0)
	.p2align 3
	s_setprio 1
	s_barrier
	v_mfma_f32_16x16x32_bf16 v[30:33], v[66:69], v[162:165], v[30:33]
	v_mfma_f32_16x16x32_bf16 v[30:33], v[70:73], v[166:169], v[30:33]
	v_mfma_f32_16x16x32_bf16 v[26:29], v[66:69], v[170:173], v[26:29]
	v_mfma_f32_16x16x32_bf16 v[26:29], v[70:73], v[174:177], v[26:29]
	v_mfma_f32_16x16x32_bf16 v[62:65], v[66:69], v[178:181], v[62:65]
	v_mfma_f32_16x16x32_bf16 v[62:65], v[70:73], v[184:187], v[62:65]
	v_mfma_f32_16x16x32_bf16 v[58:61], v[66:69], v[220:223], v[58:61]
	v_mfma_f32_16x16x32_bf16 v[58:61], v[70:73], v[224:227], v[58:61]
	v_mfma_f32_16x16x32_bf16 v[50:53], v[82:85], v[220:223], v[50:53]
	v_mfma_f32_16x16x32_bf16 v[50:53], v[142:145], v[224:227], v[50:53]
	v_mfma_f32_16x16x32_bf16 v[54:57], v[82:85], v[178:181], v[54:57]
	v_mfma_f32_16x16x32_bf16 v[54:57], v[142:145], v[184:187], v[54:57]
	v_mfma_f32_16x16x32_bf16 v[18:21], v[82:85], v[170:173], v[18:21]
	v_mfma_f32_16x16x32_bf16 v[18:21], v[142:145], v[174:177], v[18:21]
	v_mfma_f32_16x16x32_bf16 v[22:25], v[82:85], v[162:165], v[22:25]
	v_mfma_f32_16x16x32_bf16 v[22:25], v[142:145], v[166:169], v[22:25]
	v_mfma_f32_16x16x32_bf16 v[14:17], v[146:149], v[162:165], v[14:17]
	v_mfma_f32_16x16x32_bf16 v[14:17], v[150:153], v[166:169], v[14:17]
	v_mfma_f32_16x16x32_bf16 v[10:13], v[146:149], v[170:173], v[10:13]
	v_mfma_f32_16x16x32_bf16 v[10:13], v[150:153], v[174:177], v[10:13]
	v_mfma_f32_16x16x32_bf16 v[46:49], v[146:149], v[178:181], v[46:49]
	v_mfma_f32_16x16x32_bf16 v[46:49], v[150:153], v[184:187], v[46:49]
	v_mfma_f32_16x16x32_bf16 v[38:41], v[146:149], v[220:223], v[38:41]
	v_mfma_f32_16x16x32_bf16 v[38:41], v[150:153], v[224:227], v[38:41]
	v_mfma_f32_16x16x32_bf16 v[42:45], v[154:157], v[220:223], v[42:45]
	v_mfma_f32_16x16x32_bf16 v[42:45], v[158:161], v[224:227], v[42:45]
	v_mfma_f32_16x16x32_bf16 v[34:37], v[154:157], v[178:181], v[34:37]
	v_mfma_f32_16x16x32_bf16 v[34:37], v[158:161], v[184:187], v[34:37]
	v_mfma_f32_16x16x32_bf16 v[2:5], v[154:157], v[170:173], v[2:5]
	v_mfma_f32_16x16x32_bf16 v[2:5], v[158:161], v[174:177], v[2:5]
	v_mfma_f32_16x16x32_bf16 v[6:9], v[154:157], v[162:165], v[6:9]
	v_mfma_f32_16x16x32_bf16 v[6:9], v[158:161], v[166:169], v[6:9]
	s_barrier
	s_setprio 0
	s_add_i32 s0, s0, 2
	s_add_u32 s66, s66, 0x100
	s_addc_u32 s67, s67, 0
	s_cmp_gt_u32 s0, 29
	s_mov_b64 s[12:13], s[96:97]
	s_mov_b32 s101, 0
	s_cbranch_scc0 .LBB0_1327
	s_branch .Lrlx_f1_x

; #define PG8_STAGE(bufoff, gbase, voff) do { _Pragma("unroll") for (int _i = 0; _i < 2; ++_i) \
;         __builtin_amdgcn_global_load_lds((const unsigned*)((const char*)(gbase) + (voff)[_i]), (PG8_LAS unsigned*)(lds + (bufoff) + ldsw + _i * 8192), 16, 0, 0); } while (0)
; #define PG8_LDA(dst, b, h) do { _Pragma("unroll") for (int m = 0; m < 4; ++m) _Pragma("unroll") for (int k = 0; k < 2; ++k) dst[m][k] = *(const PG8_LAS bf16x8*)(lds + PG8_SA(b, h) + aoff + m * 2048 + k * 1024); } while (0)
; #define PG8_LDB(dst, b, h) do { _Pragma("unroll") for (int n = 0; n < 2; ++n) _Pragma("unroll") for (int k = 0; k < 2; ++k) dst[n][k] = *(const PG8_LAS bf16x8*)(lds + PG8_SB(b, h) + boff + n * 2048 + k * 1024); } while (0)
; #define PG8_WAIT_L(n) asm volatile("s_waitcnt lgkmcnt(" #n ")" ::: "memory")
; #define PG8_WAIT_V_SEL(sel) asm volatile("s_cmp_eq_u32 %0, 0\n\ts_cbranch_scc1 .Lw8_%=\n\ts_waitcnt vmcnt(22)\n\ts_branch .Lwd_%=\n.Lw8_%=:\n\ts_waitcnt vmcnt(8)\n.Lwd_%=:" :: "s"(sel) : "memory", "scc")
; #define PG8_BAR __builtin_amdgcn_s_barrier()
; #define PG8_SCHED __builtin_amdgcn_sched_barrier(0)
;     ...
;             const bool last = (t == nt * KREP - 2);
;             const int t1w = KREP > 1 ? ((t + 1) & (nt - 1)) : t + 1, t2w = KREP > 1 ? ((t + 2) & (nt - 1)) : t + 2;
;             const char* a1 = cA + (size_t)t1w * kstep;
;             const char* a2 = last ? nA : cA + (size_t)t2w * kstep; const char* b2 = last ? nB : cB + (size_t)t2w * kstep;
;             const char* a3 = a2 + kstep; const char* b3 = b2 + kstep;
;             if (last && has_next) S.a_ready(nxt);
;             const int relax = __builtin_amdgcn_readfirstlane((MK_RELAXW && t == 0 && ui > 0) ? 1 : 0);
;             if constexpr (SP2) {
;             PG8_LDB(B0, 0, 0); PG8_LDB(B1, 0, 1); PG8_SCHED; PG8_LDA(At, 0, 0); PG8_STAGE(PG8_SA(1, 1), a1 + hstep, voffA);
;             PG8_WAIT_V_SEL(relax);
;             PG8_WAIT_L(0); PG8_BAR; PG8_MMA(0, 0, At, B0); PG8_MMA(0, 1, At, B1); PG8_BAR; PG8_SCHED;
;             PG8_LDA(At, 0, 1); PG8_STAGE(PG8_SB(0, 0), b2, voffB); PG8_STAGE(PG8_SB(0, 1), b2 + hstep, voffB); PG8_STAGE(PG8_SA(0, 0), a2, voffA);
;             PG8_WAIT_V_SEL(relax);
;             PG8_WAIT_L(0); PG8_BAR; PG8_MMA(1, 0, At, B0); PG8_MMA(1, 1, At, B1); PG8_BAR; PG8_SCHED;
.LBB0_1648:
	s_add_u32 s10, s8, 0x100
	s_addc_u32 s11, s9, 0
	s_add_i32 s46, 0, 0x10000
	s_cmpk_eq_i32 s45, 0x52
	s_cselect_b32 s41, s1, s11
	s_cselect_b32 s40, s0, s10
	s_cselect_b32 s81, s79, s44
	s_cselect_b32 s80, s78, s37
	s_add_i32 s47, 0, 0x14000
	ds_read_b128 v[58:61], v206
	ds_read_b128 v[62:65], v206 offset:1024
	ds_read_b128 v[74:77], v206 offset:2048
	ds_read_b128 v[78:81], v206 offset:3072
	ds_read_b128 v[130:133], v206 offset:16384
	ds_read_b128 v[142:145], v206 offset:17408
	ds_read_b128 v[154:157], v206 offset:18432
	ds_read_b128 v[158:161], v206 offset:19456
	s_add_i32 m0, s91, 0xc000
	ds_read_b128 v[162:165], v246
	ds_read_b128 v[166:169], v246 offset:1024
	ds_read_b128 v[170:173], v246 offset:2048
	ds_read_b128 v[174:177], v246 offset:3072
	ds_read_b128 v[184:187], v246 offset:4096
	ds_read_b128 v[194:197], v246 offset:5120
	ds_read_b128 v[198:201], v246 offset:6144
	ds_read_b128 v[202:205], v246 offset:7168
	global_load_lds_dwordx4 v190, s[8:9]
	s_add_i32 m0, s91, 0xe000
	s_nop 0
	global_load_lds_dwordx4 v192, s[8:9]
	s_waitcnt vmcnt(8)
	s_waitcnt lgkmcnt(0)
	.p2align 3
	s_setprio 1
	s_barrier
	v_mfma_f32_16x16x32_bf16 v[150:153], v[58:61], v[162:165], v[150:153]
	v_mfma_f32_16x16x32_bf16 v[150:153], v[62:65], v[166:169], v[150:153]
	v_mfma_f32_16x16x32_bf16 v[126:129], v[58:61], v[170:173], v[126:129]
	v_mfma_f32_16x16x32_bf16 v[126:129], v[62:65], v[174:177], v[126:129]
	v_mfma_f32_16x16x32_bf16 v[110:113], v[58:61], v[184:187], v[110:113]
	v_mfma_f32_16x16x32_bf16 v[110:113], v[62:65], v[194:197], v[110:113]
	v_mfma_f32_16x16x32_bf16 v[94:97], v[58:61], v[198:201], v[94:97]
	v_mfma_f32_16x16x32_bf16 v[94:97], v[62:65], v[202:205], v[94:97]
	v_mfma_f32_16x16x32_bf16 v[90:93], v[74:77], v[198:201], v[90:93]
	v_mfma_f32_16x16x32_bf16 v[90:93], v[78:81], v[202:205], v[90:93]
	v_mfma_f32_16x16x32_bf16 v[106:109], v[74:77], v[184:187], v[106:109]
	v_mfma_f32_16x16x32_bf16 v[106:109], v[78:81], v[194:197], v[106:109]
	v_mfma_f32_16x16x32_bf16 v[122:125], v[74:77], v[170:173], v[122:125]
	v_mfma_f32_16x16x32_bf16 v[122:125], v[78:81], v[174:177], v[122:125]
	v_mfma_f32_16x16x32_bf16 v[146:149], v[74:77], v[162:165], v[146:149]
	v_mfma_f32_16x16x32_bf16 v[146:149], v[78:81], v[166:169], v[146:149]
	v_mfma_f32_16x16x32_bf16 v[138:141], v[130:133], v[162:165], v[138:141]
	v_mfma_f32_16x16x32_bf16 v[138:141], v[142:145], v[166:169], v[138:141]
	v_mfma_f32_16x16x32_bf16 v[118:121], v[130:133], v[170:173], v[118:121]
	v_mfma_f32_16x16x32_bf16 v[118:121], v[142:145], v[174:177], v[118:121]
	v_mfma_f32_16x16x32_bf16 v[102:105], v[130:133], v[184:187], v[102:105]
	v_mfma_f32_16x16x32_bf16 v[102:105], v[142:145], v[194:197], v[102:105]
	v_mfma_f32_16x16x32_bf16 v[86:89], v[130:133], v[198:201], v[86:89]
	v_mfma_f32_16x16x32_bf16 v[86:89], v[142:145], v[202:205], v[86:89]
	v_mfma_f32_16x16x32_bf16 v[82:85], v[154:157], v[198:201], v[82:85]
	v_mfma_f32_16x16x32_bf16 v[82:85], v[158:161], v[202:205], v[82:85]
	v_mfma_f32_16x16x32_bf16 v[98:101], v[154:157], v[184:187], v[98:101]
	v_mfma_f32_16x16x32_bf16 v[98:101], v[158:161], v[194:197], v[98:101]
	v_mfma_f32_16x16x32_bf16 v[114:117], v[154:157], v[170:173], v[114:117]
	v_mfma_f32_16x16x32_bf16 v[114:117], v[158:161], v[174:177], v[114:117]
	v_mfma_f32_16x16x32_bf16 v[134:137], v[154:157], v[162:165], v[134:137]
	v_mfma_f32_16x16x32_bf16 v[134:137], v[158:161], v[166:169], v[134:137]
	s_barrier
	s_setprio 0
	s_add_i32 s8, s46, s90
	s_mov_b32 m0, s8
	ds_read_b128 v[162:165], v246 offset:16384
	ds_read_b128 v[166:169], v246 offset:17408
	ds_read_b128 v[170:173], v246 offset:18432
	ds_read_b128 v[174:177], v246 offset:19456
	ds_read_b128 v[184:187], v246 offset:20480
	ds_read_b128 v[194:197], v246 offset:21504
	ds_read_b128 v[198:201], v246 offset:22528
	ds_read_b128 v[202:205], v246 offset:23552
	global_load_lds_dwordx4 v182, s[80:81]
	s_add_i32 m0, s8, 0x2000
	s_add_u32 s8, s80, 0x158000
	s_addc_u32 s9, s81, 0
	s_add_i32 s46, s47, s90
	global_load_lds_dwordx4 v188, s[80:81]
	s_mov_b32 m0, s46
	s_nop 0
	global_load_lds_dwordx4 v182, s[8:9]
	s_add_i32 m0, s46, 0x2000
	s_nop 0
	global_load_lds_dwordx4 v188, s[8:9]
	s_mov_b32 m0, s91
	s_nop 0
	global_load_lds_dwordx4 v178, s[40:41]
	s_mov_b32 m0, s92
	s_nop 0
	global_load_lds_dwordx4 v180, s[40:41]
	s_waitcnt vmcnt(8)
	s_waitcnt lgkmcnt(0)
	.p2align 3
	s_setprio 1
	s_barrier
	v_mfma_f32_16x16x32_bf16 v[70:73], v[58:61], v[162:165], v[70:73]
	v_mfma_f32_16x16x32_bf16 v[70:73], v[62:65], v[166:169], v[70:73]
	v_mfma_f32_16x16x32_bf16 v[46:49], v[58:61], v[170:173], v[46:49]
	v_mfma_f32_16x16x32_bf16 v[46:49], v[62:65], v[174:177], v[46:49]
	v_mfma_f32_16x16x32_bf16 v[30:33], v[58:61], v[184:187], v[30:33]
	v_mfma_f32_16x16x32_bf16 v[30:33], v[62:65], v[194:197], v[30:33]
	v_mfma_f32_16x16x32_bf16 v[14:17], v[58:61], v[198:201], v[14:17]
	v_mfma_f32_16x16x32_bf16 v[14:17], v[62:65], v[202:205], v[14:17]
	v_mfma_f32_16x16x32_bf16 v[10:13], v[74:77], v[198:201], v[10:13]
	v_mfma_f32_16x16x32_bf16 v[10:13], v[78:81], v[202:205], v[10:13]
	v_mfma_f32_16x16x32_bf16 v[26:29], v[74:77], v[184:187], v[26:29]
	v_mfma_f32_16x16x32_bf16 v[26:29], v[78:81], v[194:197], v[26:29]
	v_mfma_f32_16x16x32_bf16 v[42:45], v[74:77], v[170:173], v[42:45]
	v_mfma_f32_16x16x32_bf16 v[42:45], v[78:81], v[174:177], v[42:45]
	v_mfma_f32_16x16x32_bf16 v[66:69], v[74:77], v[162:165], v[66:69]
	v_mfma_f32_16x16x32_bf16 v[66:69], v[78:81], v[166:169], v[66:69]
	v_mfma_f32_16x16x32_bf16 v[54:57], v[130:133], v[162:165], v[54:57]
	v_mfma_f32_16x16x32_bf16 v[54:57], v[142:145], v[166:169], v[54:57]
	v_mfma_f32_16x16x32_bf16 v[38:41], v[130:133], v[170:173], v[38:41]
	v_mfma_f32_16x16x32_bf16 v[38:41], v[142:145], v[174:177], v[38:41]
	v_mfma_f32_16x16x32_bf16 v[22:25], v[130:133], v[184:187], v[22:25]
	v_mfma_f32_16x16x32_bf16 v[22:25], v[142:145], v[194:197], v[22:25]
	v_mfma_f32_16x16x32_bf16 v[6:9], v[130:133], v[198:201], v[6:9]
	v_mfma_f32_16x16x32_bf16 v[6:9], v[142:145], v[202:205], v[6:9]
	v_mfma_f32_16x16x32_bf16 v[2:5], v[154:157], v[198:201], v[2:5]
	v_mfma_f32_16x16x32_bf16 v[2:5], v[158:161], v[202:205], v[2:5]
	v_mfma_f32_16x16x32_bf16 v[18:21], v[154:157], v[184:187], v[18:21]
	v_mfma_f32_16x16x32_bf16 v[18:21], v[158:161], v[194:197], v[18:21]
	v_mfma_f32_16x16x32_bf16 v[34:37], v[154:157], v[170:173], v[34:37]
	v_mfma_f32_16x16x32_bf16 v[34:37], v[158:161], v[174:177], v[34:37]
	v_mfma_f32_16x16x32_bf16 v[50:53], v[154:157], v[162:165], v[50:53]
	v_mfma_f32_16x16x32_bf16 v[50:53], v[158:161], v[166:169], v[50:53]
	s_barrier
; #define PG8_STAGE(bufoff, gbase, voff) do { _Pragma("unroll") for (int _i = 0; _i < 2; ++_i) \
;         __builtin_amdgcn_global_load_lds((const unsigned*)((const char*)(gbase) + (voff)[_i]), (PG8_LAS unsigned*)(lds + (bufoff) + ldsw + _i * 8192), 16, 0, 0); } while (0)
; #define PG8_LDA(dst, b, h) do { _Pragma("unroll") for (int m = 0; m < 4; ++m) _Pragma("unroll") for (int k = 0; k < 2; ++k) dst[m][k] = *(const PG8_LAS bf16x8*)(lds + PG8_SA(b, h) + aoff + m * 2048 + k * 1024); } while (0)
; #define PG8_LDB(dst, b, h) do { _Pragma("unroll") for (int n = 0; n < 2; ++n) _Pragma("unroll") for (int k = 0; k < 2; ++k) dst[n][k] = *(const PG8_LAS bf16x8*)(lds + PG8_SB(b, h) + boff + n * 2048 + k * 1024); } while (0)
; #define PG8_WAIT_V(n) asm volatile("s_waitcnt vmcnt(" #n ")" ::: "memory")
; #define PG8_WAIT_L(n) asm volatile("s_waitcnt lgkmcnt(" #n ")" ::: "memory")
; #define PG8_BAR __builtin_amdgcn_s_barrier()
; #define PG8_SCHED __builtin_amdgcn_sched_barrier(0)
;     ...
;             PG8_WAIT_L(0); PG8_BAR; PG8_MMA(1, 0, At, B0); PG8_MMA(1, 1, At, B1); PG8_BAR; PG8_SCHED;
;             PG8_LDB(B0, 1, 0); PG8_LDB(B1, 1, 1); PG8_SCHED; PG8_LDA(At, 1, 0); PG8_STAGE(PG8_SA(0, 1), a2 + hstep, voffA);
;             PG8_WAIT_V(8); PG8_WAIT_L(0); PG8_BAR; PG8_MMA(0, 0, At, B0); PG8_MMA(0, 1, At, B1); PG8_BAR; PG8_SCHED;
;             PG8_LDA(At, 1, 1); PG8_STAGE(PG8_SB(1, 0), b3, voffB); PG8_STAGE(PG8_SB(1, 1), b3 + hstep, voffB); PG8_STAGE(PG8_SA(1, 0), a3, voffA);
;             PG8_WAIT_V(8); PG8_WAIT_L(0); PG8_BAR; PG8_MMA(1, 0, At, B0); PG8_MMA(1, 1, At, B1); PG8_BAR; PG8_SCHED;
	s_setprio 0
	s_add_i32 s46, 0, 0x18000
	s_add_i32 s47, 0, 0x1c000
	ds_read_b128 v[58:61], v206 offset:32768
	ds_read_b128 v[62:65], v206 offset:33792
	ds_read_b128 v[74:77], v206 offset:34816
	ds_read_b128 v[78:81], v206 offset:35840
	ds_read_b128 v[130:133], v206 offset:49152
	ds_read_b128 v[142:145], v206 offset:50176
	ds_read_b128 v[154:157], v206 offset:51200
	ds_read_b128 v[158:161], v206 offset:52224
	s_add_u32 s8, s40, 0x158000
	s_addc_u32 s9, s41, 0
	s_mov_b32 m0, s93
	ds_read_b128 v[162:165], v246 offset:32768
	ds_read_b128 v[166:169], v246 offset:33792
	ds_read_b128 v[170:173], v246 offset:34816
	ds_read_b128 v[174:177], v246 offset:35840
	ds_read_b128 v[184:187], v246 offset:36864
	ds_read_b128 v[194:197], v246 offset:37888
	ds_read_b128 v[198:201], v246 offset:38912
	ds_read_b128 v[202:205], v246 offset:39936
	global_load_lds_dwordx4 v178, s[8:9]
	s_mov_b32 m0, s94
	s_nop 0
	global_load_lds_dwordx4 v180, s[8:9]
	s_waitcnt vmcnt(8)
	s_waitcnt lgkmcnt(0)
	.p2align 3
	s_setprio 1
	s_barrier
	v_mfma_f32_16x16x32_bf16 v[150:153], v[58:61], v[162:165], v[150:153]
	v_mfma_f32_16x16x32_bf16 v[150:153], v[62:65], v[166:169], v[150:153]
	v_mfma_f32_16x16x32_bf16 v[126:129], v[58:61], v[170:173], v[126:129]
	v_mfma_f32_16x16x32_bf16 v[126:129], v[62:65], v[174:177], v[126:129]
	v_mfma_f32_16x16x32_bf16 v[110:113], v[58:61], v[184:187], v[110:113]
	v_mfma_f32_16x16x32_bf16 v[110:113], v[62:65], v[194:197], v[110:113]
	v_mfma_f32_16x16x32_bf16 v[94:97], v[58:61], v[198:201], v[94:97]
	v_mfma_f32_16x16x32_bf16 v[94:97], v[62:65], v[202:205], v[94:97]
	v_mfma_f32_16x16x32_bf16 v[90:93], v[74:77], v[198:201], v[90:93]
	v_mfma_f32_16x16x32_bf16 v[90:93], v[78:81], v[202:205], v[90:93]
	v_mfma_f32_16x16x32_bf16 v[106:109], v[74:77], v[184:187], v[106:109]
	v_mfma_f32_16x16x32_bf16 v[106:109], v[78:81], v[194:197], v[106:109]
	v_mfma_f32_16x16x32_bf16 v[122:125], v[74:77], v[170:173], v[122:125]
	v_mfma_f32_16x16x32_bf16 v[122:125], v[78:81], v[174:177], v[122:125]
	v_mfma_f32_16x16x32_bf16 v[146:149], v[74:77], v[162:165], v[146:149]
	v_mfma_f32_16x16x32_bf16 v[146:149], v[78:81], v[166:169], v[146:149]
	v_mfma_f32_16x16x32_bf16 v[138:141], v[130:133], v[162:165], v[138:141]
	v_mfma_f32_16x16x32_bf16 v[138:141], v[142:145], v[166:169], v[138:141]
	v_mfma_f32_16x16x32_bf16 v[118:121], v[130:133], v[170:173], v[118:121]
	v_mfma_f32_16x16x32_bf16 v[118:121], v[142:145], v[174:177], v[118:121]
	v_mfma_f32_16x16x32_bf16 v[102:105], v[130:133], v[184:187], v[102:105]
	v_mfma_f32_16x16x32_bf16 v[102:105], v[142:145], v[194:197], v[102:105]
	v_mfma_f32_16x16x32_bf16 v[86:89], v[130:133], v[198:201], v[86:89]
	v_mfma_f32_16x16x32_bf16 v[86:89], v[142:145], v[202:205], v[86:89]
	v_mfma_f32_16x16x32_bf16 v[82:85], v[154:157], v[198:201], v[82:85]
	v_mfma_f32_16x16x32_bf16 v[82:85], v[158:161], v[202:205], v[82:85]
	v_mfma_f32_16x16x32_bf16 v[98:101], v[154:157], v[184:187], v[98:101]
	v_mfma_f32_16x16x32_bf16 v[98:101], v[158:161], v[194:197], v[98:101]
	v_mfma_f32_16x16x32_bf16 v[114:117], v[154:157], v[170:173], v[114:117]
	v_mfma_f32_16x16x32_bf16 v[114:117], v[158:161], v[174:177], v[114:117]
	v_mfma_f32_16x16x32_bf16 v[134:137], v[154:157], v[162:165], v[134:137]
	v_mfma_f32_16x16x32_bf16 v[134:137], v[158:161], v[166:169], v[134:137]
	s_barrier
	s_setprio 0
	s_add_i32 s8, s46, s90
	s_mov_b32 m0, s8
	ds_read_b128 v[162:165], v246 offset:49152
	ds_read_b128 v[166:169], v246 offset:50176
	ds_read_b128 v[170:173], v246 offset:51200
	ds_read_b128 v[174:177], v246 offset:52224
	ds_read_b128 v[184:187], v246 offset:53248
	ds_read_b128 v[194:197], v246 offset:54272
	ds_read_b128 v[198:201], v246 offset:55296
	ds_read_b128 v[202:205], v246 offset:56320
	s_add_u32 s100, s80, 0x80
	s_addc_u32 s101, s81, 0
	global_load_lds_dwordx4 v182, s[100:101]
	s_add_i32 m0, s8, 0x2000
	s_add_u32 s8, s80, 0x158080
	s_addc_u32 s9, s81, 0
	s_add_i32 vcc_lo, s47, s90
	global_load_lds_dwordx4 v188, s[100:101]
	s_mov_b32 m0, vcc_lo
	s_nop 0
	global_load_lds_dwordx4 v182, s[8:9]
	s_add_i32 m0, vcc_lo, 0x2000
	s_nop 0
	global_load_lds_dwordx4 v188, s[8:9]
	s_mov_b32 m0, s31
	s_nop 0
	s_add_u32 s100, s40, 0x80
	s_addc_u32 s101, s41, 0
	global_load_lds_dwordx4 v178, s[100:101]
	s_mov_b32 m0, s56
	s_nop 0
	global_load_lds_dwordx4 v180, s[100:101]
	s_waitcnt vmcnt(8)
	s_waitcnt lgkmcnt(0)
	.p2align 3
	s_setprio 1
	s_barrier
	v_mfma_f32_16x16x32_bf16 v[70:73], v[58:61], v[162:165], v[70:73]
	v_mfma_f32_16x16x32_bf16 v[70:73], v[62:65], v[166:169], v[70:73]
	v_mfma_f32_16x16x32_bf16 v[46:49], v[58:61], v[170:173], v[46:49]
	v_mfma_f32_16x16x32_bf16 v[46:49], v[62:65], v[174:177], v[46:49]
	v_mfma_f32_16x16x32_bf16 v[30:33], v[58:61], v[184:187], v[30:33]
	v_mfma_f32_16x16x32_bf16 v[30:33], v[62:65], v[194:197], v[30:33]
	v_mfma_f32_16x16x32_bf16 v[14:17], v[58:61], v[198:201], v[14:17]
	v_mfma_f32_16x16x32_bf16 v[14:17], v[62:65], v[202:205], v[14:17]
	v_mfma_f32_16x16x32_bf16 v[10:13], v[74:77], v[198:201], v[10:13]
	v_mfma_f32_16x16x32_bf16 v[10:13], v[78:81], v[202:205], v[10:13]
	v_mfma_f32_16x16x32_bf16 v[26:29], v[74:77], v[184:187], v[26:29]
	v_mfma_f32_16x16x32_bf16 v[26:29], v[78:81], v[194:197], v[26:29]
	v_mfma_f32_16x16x32_bf16 v[42:45], v[74:77], v[170:173], v[42:45]
	v_mfma_f32_16x16x32_bf16 v[42:45], v[78:81], v[174:177], v[42:45]
	v_mfma_f32_16x16x32_bf16 v[66:69], v[74:77], v[162:165], v[66:69]
	v_mfma_f32_16x16x32_bf16 v[66:69], v[78:81], v[166:169], v[66:69]
	v_mfma_f32_16x16x32_bf16 v[54:57], v[130:133], v[162:165], v[54:57]
	v_mfma_f32_16x16x32_bf16 v[54:57], v[142:145], v[166:169], v[54:57]
	v_mfma_f32_16x16x32_bf16 v[38:41], v[130:133], v[170:173], v[38:41]
	v_mfma_f32_16x16x32_bf16 v[38:41], v[142:145], v[174:177], v[38:41]
	v_mfma_f32_16x16x32_bf16 v[22:25], v[130:133], v[184:187], v[22:25]
	v_mfma_f32_16x16x32_bf16 v[22:25], v[142:145], v[194:197], v[22:25]
	v_mfma_f32_16x16x32_bf16 v[6:9], v[130:133], v[198:201], v[6:9]
	v_mfma_f32_16x16x32_bf16 v[6:9], v[142:145], v[202:205], v[6:9]
	v_mfma_f32_16x16x32_bf16 v[2:5], v[154:157], v[198:201], v[2:5]
	v_mfma_f32_16x16x32_bf16 v[2:5], v[158:161], v[202:205], v[2:5]
	v_mfma_f32_16x16x32_bf16 v[18:21], v[154:157], v[184:187], v[18:21]
	v_mfma_f32_16x16x32_bf16 v[18:21], v[158:161], v[194:197], v[18:21]
	v_mfma_f32_16x16x32_bf16 v[34:37], v[154:157], v[170:173], v[34:37]
	v_mfma_f32_16x16x32_bf16 v[34:37], v[158:161], v[174:177], v[34:37]
	v_mfma_f32_16x16x32_bf16 v[50:53], v[154:157], v[162:165], v[50:53]
	v_mfma_f32_16x16x32_bf16 v[50:53], v[158:161], v[166:169], v[50:53]
	s_barrier
	s_setprio 0
	s_add_i32 s45, s45, 2
	s_add_u32 s37, s37, 0x100
	s_addc_u32 s44, s44, 0
	s_cmpk_gt_u32 s45, 0x53
	s_mov_b64 s[8:9], s[10:11]
	s_cbranch_scc0 .LBB0_1648
	s_and_b64 vcc, exec, s[76:77]
	s_cbranch_vccz .LBB0_1651
	s_barrier
